# one static s_setprio 1 for waves 4-7 per GEMM phase, all 64 per-phase priority flips deleted
# speedup vs baseline: 1.0029x; 1.0029x over previous
.Lhf_done:
	s_barrier
	s_cmp_lt_u32 s86, 0x100
	s_cbranch_scc1 .Lprio_a
	s_setprio 1
.Lprio_a:
	s_cmp_eq_u32 s51, 1
	s_cbranch_scc1 .LBB0_408
	s_mov_b64 s[8:9], s[66:67]
	v_mov_b32_e32 v0, v1
	s_load_dwordx2 s[10:11], s[8:9], 0x100
	v_mbcnt_lo_u32_b32 v0, -1, v0
	v_mbcnt_hi_u32_b32 v144, -1, v0
	v_readlane_b32 s0, v254, 8
	v_add_u32_e32 v0, s86, v144
	v_readlane_b32 s1, v254, 9
	s_lshr_b32 s52, s51, 1
	v_readfirstlane_b32 s4, v0
	s_andn2_b64 vcc, exec, s[0:1]
	v_readlane_b32 s0, v255, 16
	s_ashr_i32 s30, s4, 6
	s_add_i32 s52, s52, s0
	s_cbranch_vccnz .LBB0_410
	v_lshlrev_b32_e32 v2, 4, v0
	v_add_u32_e32 v3, 0x2000, v2
	v_ashrrev_i32_e32 v4, 31, v3
	v_lshrrev_b32_e32 v4, 22, v4
	v_add_u32_e32 v4, v3, v4
	v_ashrrev_i32_e32 v10, 10, v4
	v_mul_i32_i24_e32 v4, 0x400, v10
	v_sub_u32_e32 v3, v3, v4
	v_lshrrev_b32_e32 v4, 4, v3
	v_bitop3_b32 v3, v4, v3, 32 bitop3:0x6c
	v_ashrrev_i32_e32 v4, 31, v3
	v_lshrrev_b32_e32 v4, 26, v4
	v_add_u32_e32 v4, v3, v4
	v_lshlrev_b32_e32 v5, 3, v10
	v_ashrrev_i32_e32 v11, 6, v4
	v_and_b32_e32 v5, -16, v5
	v_add_u32_e32 v5, v11, v5
	v_and_b32_e32 v6, 3, v11
	s_mov_b32 s6, 0x1fffe0
	v_lshrrev_b32_e32 v7, 2, v5
	v_lshlrev_b32_e32 v8, 1, v5
	v_and_b32_e32 v4, 0xc0, v4
	v_and_or_b32 v6, v5, s6, v6
	v_and_b32_e32 v7, 4, v7
	v_and_b32_e32 v8, 24, v8
	v_sub_u32_e32 v3, v3, v4
	v_or3_b32 v6, v6, v7, v8
	v_lshlrev_b32_e32 v7, 5, v10
	v_ashrrev_i16_sdwa v3, v236, sext(v3) dst_sel:DWORD dst_unused:UNUSED_PAD src0_sel:DWORD src1_sel:BYTE_0
	v_and_b32_e32 v7, 32, v7
	v_bfe_i32 v12, v3, 0, 16
	v_add_lshl_u32 v3, v7, v12, 1
	v_lshl_add_u32 v130, v6, 11, v3
	v_lshl_add_u32 v132, v5, 11, v3
	v_bfe_i32 v3, v0, 27, 1
	v_lshrrev_b32_e32 v3, 22, v3
	v_add_u32_e32 v3, v2, v3
	v_and_b32_e32 v3, 0xfffffc00, v3
	v_sub_u32_e32 v2, v2, v3
	v_lshrrev_b32_e32 v3, 4, v2
	v_ashrrev_i32_e32 v4, 31, v0
	v_bitop3_b32 v2, v3, v2, 32 bitop3:0x6c
	v_lshrrev_b32_e32 v4, 26, v4
	v_ashrrev_i32_e32 v3, 31, v2
	v_add_u32_e32 v0, v0, v4
	v_lshrrev_b32_e32 v3, 26, v3
	v_ashrrev_i32_e32 v14, 6, v0
	v_add_u32_e32 v3, v2, v3
	v_lshlrev_b32_e32 v0, 3, v14
	v_ashrrev_i32_e32 v13, 6, v3
	v_and_b32_e32 v0, -16, v0
	s_waitcnt lgkmcnt(0)
	s_add_u32 s0, s10, 0x5c00000
	v_add_u32_e32 v4, v13, v0
	s_addc_u32 s1, s11, 0
	s_mul_i32 s2, s52, 0xb00000
	v_and_b32_e32 v0, 3, v13
	v_lshrrev_b32_e32 v5, 2, v4
	v_lshlrev_b32_e32 v6, 1, v4
	v_and_b32_e32 v3, 0xc0, v3
	s_mul_hi_u32 s3, s52, 0xb00000
	s_add_u32 s2, s10, s2
	v_and_or_b32 v0, v4, s6, v0
	v_and_b32_e32 v5, 4, v5
	v_and_b32_e32 v6, 24, v6
	v_sub_u32_e32 v2, v2, v3
	s_addc_u32 s3, s11, s3
	s_ashr_i32 s5, s4, 8
	s_lshl_b32 s31, s30, 10
	v_or3_b32 v0, v0, v5, v6
	v_lshlrev_b32_e32 v5, 5, v14
	v_ashrrev_i16_sdwa v2, v236, sext(v2) dst_sel:DWORD dst_unused:UNUSED_PAD src0_sel:DWORD src1_sel:BYTE_0
	v_readlane_b32 s6, v254, 15
	v_and_b32_e32 v5, 32, v5
	v_bfe_i32 v15, v2, 0, 16
	v_readlane_b32 s7, v254, 16
	s_add_u32 s24, s2, s6
	v_add_lshl_u32 v2, v5, v15, 1
	s_addc_u32 s25, s3, s7
	s_add_i32 s33, s31, 0
	v_lshl_add_u32 v0, v0, 11, v2
	s_add_i32 m0, s33, 0x10000
	v_readlane_b32 s6, v254, 13
	global_load_lds_dwordx4 v0, s[24:25]
	s_add_i32 m0, s33, 0x12000
	v_readlane_b32 s7, v254, 14
	s_add_u32 s26, s0, s6
	s_addc_u32 s27, s1, s7
	s_add_u32 s6, s24, 0x40000
	global_load_lds_dwordx4 v130, s[24:25]
	s_addc_u32 s7, s25, 0
	s_add_i32 m0, s33, 0x14000
	s_add_i32 s34, s33, 0x2000
	global_load_lds_dwordx4 v0, s[6:7]
	s_add_i32 m0, s33, 0x16000
	v_lshl_add_u32 v134, v4, 11, v2
	global_load_lds_dwordx4 v130, s[6:7]
	s_mov_b32 m0, s33
	s_add_u32 s6, s26, 0x40000
	global_load_lds_dwordx4 v134, s[26:27]
	s_mov_b32 m0, s34
	s_addc_u32 s7, s27, 0
	s_add_i32 s35, s33, 0x4000
	global_load_lds_dwordx4 v132, s[26:27]
	s_mov_b32 m0, s35
	s_add_i32 s36, s33, 0x6000
	global_load_lds_dwordx4 v134, s[6:7]
	s_mov_b32 m0, s36
	v_mov_b32_e32 v131, v1
	global_load_lds_dwordx4 v132, s[6:7]
	v_mov_b32_e32 v135, v1
	v_mov_b32_e32 v133, v1
	s_cmp_eq_u32 s5, 1
	v_lshl_add_u64 v[8:9], s[24:25], 0, v[0:1]
	v_lshl_add_u64 v[6:7], s[24:25], 0, v[130:131]
	v_lshl_add_u64 v[2:3], s[26:27], 0, v[134:135]
	s_cselect_b64 s[14:15], -1, 0
	s_cmp_lg_u32 s5, 1
	v_lshl_add_u64 v[4:5], s[26:27], 0, v[132:133]
	s_cbranch_scc1 .LBB0_392
	s_barrier

.LBB0_402:
	s_add_u32 s26, s24, 0xfffc0080
	s_addc_u32 s27, s25, -1
	s_add_i32 s46, 0, 0x10000
	s_cmp_eq_u32 s44, 12
	s_cselect_b32 s29, s7, s27
	s_cselect_b32 s28, s6, s26
	v_add_u32_e32 v149, s46, v146
	s_cselect_b32 s27, s23, s43
	s_cselect_b32 s26, s22, s21
	s_add_i32 s48, 0, 0x14000
	ds_read_b128 v[140:143], v149
	ds_read_b128 v[150:153], v149 offset:1024
	ds_read_b128 v[154:157], v149 offset:2048
	ds_read_b128 v[158:161], v149 offset:3072
	v_add_u32_e32 v149, s48, v146
	ds_read_b128 v[162:165], v149
	ds_read_b128 v[166:169], v149 offset:1024
	ds_read_b128 v[170:173], v149 offset:2048
	ds_read_b128 v[174:177], v149 offset:3072
	v_lshl_add_u64 v[184:185], s[24:25], 0, v[138:139]
	s_add_i32 m0, s33, 0xc000
	ds_read_b128 v[178:181], v148
	ds_read_b128 v[188:191], v148 offset:1024
	ds_read_b128 v[192:195], v148 offset:2048
	ds_read_b128 v[196:199], v148 offset:3072
	ds_read_b128 v[200:203], v148 offset:4096
	ds_read_b128 v[204:207], v148 offset:5120
	ds_read_b128 v[208:211], v148 offset:6144
	ds_read_b128 v[212:215], v148 offset:7168
	global_load_lds_dwordx4 v[184:185], off
	v_lshl_add_u64 v[184:185], s[24:25], 0, v[136:137]
	s_add_i32 m0, s33, 0xe000
	s_nop 0
	global_load_lds_dwordx4 v[184:185], off
	s_waitcnt vmcnt(8)
	s_waitcnt lgkmcnt(0)
	s_barrier
	s_waitcnt lgkmcnt(0)
	v_mfma_f32_16x16x32_bf16 v[126:129], v[140:143], v[178:181], v[126:129]
	v_mfma_f32_16x16x32_bf16 v[118:121], v[154:157], v[178:181], v[118:121]
	v_mfma_f32_16x16x32_bf16 v[110:113], v[140:143], v[192:195], v[110:113]
	v_mfma_f32_16x16x32_bf16 v[102:105], v[154:157], v[192:195], v[102:105]
	v_mfma_f32_16x16x32_bf16 v[94:97], v[140:143], v[200:203], v[94:97]
	v_mfma_f32_16x16x32_bf16 v[86:89], v[154:157], v[200:203], v[86:89]
	v_mfma_f32_16x16x32_bf16 v[78:81], v[140:143], v[208:211], v[78:81]
	v_mfma_f32_16x16x32_bf16 v[70:73], v[154:157], v[208:211], v[70:73]
	v_mfma_f32_16x16x32_bf16 v[126:129], v[150:153], v[188:191], v[126:129]
	v_mfma_f32_16x16x32_bf16 v[118:121], v[158:161], v[188:191], v[118:121]
	v_mfma_f32_16x16x32_bf16 v[110:113], v[150:153], v[196:199], v[110:113]
	v_mfma_f32_16x16x32_bf16 v[102:105], v[158:161], v[196:199], v[102:105]
	v_mfma_f32_16x16x32_bf16 v[94:97], v[150:153], v[204:207], v[94:97]
	v_mfma_f32_16x16x32_bf16 v[86:89], v[158:161], v[204:207], v[86:89]
	v_mfma_f32_16x16x32_bf16 v[78:81], v[150:153], v[212:215], v[78:81]
	v_mfma_f32_16x16x32_bf16 v[70:73], v[158:161], v[212:215], v[70:73]
	v_mfma_f32_16x16x32_bf16 v[122:125], v[162:165], v[178:181], v[122:125]
	v_mfma_f32_16x16x32_bf16 v[114:117], v[170:173], v[178:181], v[114:117]
	v_mfma_f32_16x16x32_bf16 v[106:109], v[162:165], v[192:195], v[106:109]
	v_mfma_f32_16x16x32_bf16 v[98:101], v[170:173], v[192:195], v[98:101]
	v_mfma_f32_16x16x32_bf16 v[90:93], v[162:165], v[200:203], v[90:93]
	v_mfma_f32_16x16x32_bf16 v[82:85], v[170:173], v[200:203], v[82:85]
	v_mfma_f32_16x16x32_bf16 v[74:77], v[162:165], v[208:211], v[74:77]
	v_mfma_f32_16x16x32_bf16 v[66:69], v[170:173], v[208:211], v[66:69]
	v_mfma_f32_16x16x32_bf16 v[122:125], v[166:169], v[188:191], v[122:125]
	v_mfma_f32_16x16x32_bf16 v[114:117], v[174:177], v[188:191], v[114:117]
	v_mfma_f32_16x16x32_bf16 v[106:109], v[166:169], v[196:199], v[106:109]
	v_mfma_f32_16x16x32_bf16 v[98:101], v[174:177], v[196:199], v[98:101]
	v_mfma_f32_16x16x32_bf16 v[90:93], v[166:169], v[204:207], v[90:93]
	v_mfma_f32_16x16x32_bf16 v[82:85], v[174:177], v[204:207], v[82:85]
	v_mfma_f32_16x16x32_bf16 v[74:77], v[166:169], v[212:215], v[74:77]
	v_mfma_f32_16x16x32_bf16 v[66:69], v[174:177], v[212:215], v[66:69]
	s_barrier
	s_add_i32 s46, s46, s31
	v_lshl_add_u64 v[184:185], s[26:27], 0, v[0:1]
	s_mov_b32 m0, s46
	ds_read_b128 v[178:181], v148 offset:16384
	ds_read_b128 v[188:191], v148 offset:17408
	ds_read_b128 v[192:195], v148 offset:18432
	ds_read_b128 v[196:199], v148 offset:19456
	ds_read_b128 v[200:203], v148 offset:20480
	ds_read_b128 v[204:207], v148 offset:21504
	ds_read_b128 v[208:211], v148 offset:22528
	ds_read_b128 v[212:215], v148 offset:23552
	global_load_lds_dwordx4 v[184:185], off
	s_add_i32 m0, s46, 0x2000
	s_add_u32 s46, s26, 0x40000
	v_lshl_add_u64 v[186:187], s[26:27], 0, v[130:131]
	s_addc_u32 s47, s27, 0
	s_add_i32 s48, s48, s31
	global_load_lds_dwordx4 v[186:187], off
	v_lshl_add_u64 v[216:217], s[46:47], 0, v[0:1]
	s_mov_b32 m0, s48
	v_lshl_add_u64 v[218:219], s[28:29], 0, v[132:133]
	global_load_lds_dwordx4 v[216:217], off
	v_lshl_add_u64 v[216:217], s[46:47], 0, v[130:131]
	s_add_i32 m0, s48, 0x2000
	s_nop 0
	global_load_lds_dwordx4 v[216:217], off
	v_lshl_add_u64 v[216:217], s[28:29], 0, v[134:135]
	s_mov_b32 m0, s33
	s_nop 0
	global_load_lds_dwordx4 v[216:217], off
	s_mov_b32 m0, s34
	s_nop 0
	global_load_lds_dwordx4 v[218:219], off
	s_waitcnt vmcnt(8)
	s_waitcnt lgkmcnt(0)
	s_barrier
	s_waitcnt lgkmcnt(0)
	v_mfma_f32_16x16x32_bf16 v[62:65], v[140:143], v[178:181], v[62:65]
	v_mfma_f32_16x16x32_bf16 v[54:57], v[154:157], v[178:181], v[54:57]
	v_mfma_f32_16x16x32_bf16 v[46:49], v[140:143], v[192:195], v[46:49]
	v_mfma_f32_16x16x32_bf16 v[38:41], v[154:157], v[192:195], v[38:41]
	v_mfma_f32_16x16x32_bf16 v[30:33], v[140:143], v[200:203], v[30:33]
	v_mfma_f32_16x16x32_bf16 v[22:25], v[154:157], v[200:203], v[22:25]
	v_mfma_f32_16x16x32_bf16 v[14:17], v[140:143], v[208:211], v[14:17]
	v_mfma_f32_16x16x32_bf16 v[6:9], v[154:157], v[208:211], v[6:9]
	v_mfma_f32_16x16x32_bf16 v[62:65], v[150:153], v[188:191], v[62:65]
	v_mfma_f32_16x16x32_bf16 v[54:57], v[158:161], v[188:191], v[54:57]
	v_mfma_f32_16x16x32_bf16 v[46:49], v[150:153], v[196:199], v[46:49]
	v_mfma_f32_16x16x32_bf16 v[38:41], v[158:161], v[196:199], v[38:41]
	v_mfma_f32_16x16x32_bf16 v[30:33], v[150:153], v[204:207], v[30:33]
	v_mfma_f32_16x16x32_bf16 v[22:25], v[158:161], v[204:207], v[22:25]
	v_mfma_f32_16x16x32_bf16 v[14:17], v[150:153], v[212:215], v[14:17]
	v_mfma_f32_16x16x32_bf16 v[6:9], v[158:161], v[212:215], v[6:9]
	v_mfma_f32_16x16x32_bf16 v[58:61], v[162:165], v[178:181], v[58:61]
	v_mfma_f32_16x16x32_bf16 v[50:53], v[170:173], v[178:181], v[50:53]
	v_mfma_f32_16x16x32_bf16 v[42:45], v[162:165], v[192:195], v[42:45]
	v_mfma_f32_16x16x32_bf16 v[34:37], v[170:173], v[192:195], v[34:37]
	v_mfma_f32_16x16x32_bf16 v[26:29], v[162:165], v[200:203], v[26:29]
	v_mfma_f32_16x16x32_bf16 v[18:21], v[170:173], v[200:203], v[18:21]
	v_mfma_f32_16x16x32_bf16 v[10:13], v[162:165], v[208:211], v[10:13]
	v_mfma_f32_16x16x32_bf16 v[2:5], v[170:173], v[208:211], v[2:5]
	v_mfma_f32_16x16x32_bf16 v[58:61], v[166:169], v[188:191], v[58:61]
	v_mfma_f32_16x16x32_bf16 v[50:53], v[174:177], v[188:191], v[50:53]
	v_mfma_f32_16x16x32_bf16 v[42:45], v[166:169], v[196:199], v[42:45]
	v_mfma_f32_16x16x32_bf16 v[34:37], v[174:177], v[196:199], v[34:37]
	v_mfma_f32_16x16x32_bf16 v[26:29], v[166:169], v[204:207], v[26:29]
	v_mfma_f32_16x16x32_bf16 v[18:21], v[174:177], v[204:207], v[18:21]
	v_mfma_f32_16x16x32_bf16 v[10:13], v[166:169], v[212:215], v[10:13]
	v_mfma_f32_16x16x32_bf16 v[2:5], v[174:177], v[212:215], v[2:5]
	s_barrier
	s_add_i32 s46, 0, 0x18000
	v_add_u32_e32 v149, s46, v146
	s_add_i32 s47, 0, 0x1c000
	ds_read_b128 v[140:143], v149
	ds_read_b128 v[150:153], v149 offset:1024
	ds_read_b128 v[154:157], v149 offset:2048
	ds_read_b128 v[158:161], v149 offset:3072
	v_add_u32_e32 v149, s47, v146
	ds_read_b128 v[162:165], v149
	ds_read_b128 v[166:169], v149 offset:1024
	ds_read_b128 v[170:173], v149 offset:2048
	ds_read_b128 v[174:177], v149 offset:3072
	s_add_u32 s28, s28, 0x40000
	s_addc_u32 s29, s29, 0
	s_mov_b32 m0, s35
	v_lshl_add_u64 v[220:221], s[28:29], 0, v[134:135]
	ds_read_b128 v[178:181], v148 offset:32768
	ds_read_b128 v[188:191], v148 offset:33792
	ds_read_b128 v[192:195], v148 offset:34816
	ds_read_b128 v[196:199], v148 offset:35840
	ds_read_b128 v[200:203], v148 offset:36864
	ds_read_b128 v[204:207], v148 offset:37888
	ds_read_b128 v[208:211], v148 offset:38912
	ds_read_b128 v[212:215], v148 offset:39936
	global_load_lds_dwordx4 v[220:221], off
	v_lshl_add_u64 v[220:221], s[28:29], 0, v[132:133]
	s_mov_b32 m0, s36
	s_nop 0
	global_load_lds_dwordx4 v[220:221], off
	s_waitcnt vmcnt(8)
	s_waitcnt lgkmcnt(0)
	s_barrier
	s_waitcnt lgkmcnt(0)
	v_mfma_f32_16x16x32_bf16 v[126:129], v[140:143], v[178:181], v[126:129]
	v_mfma_f32_16x16x32_bf16 v[118:121], v[154:157], v[178:181], v[118:121]
	v_mfma_f32_16x16x32_bf16 v[110:113], v[140:143], v[192:195], v[110:113]
	v_mfma_f32_16x16x32_bf16 v[102:105], v[154:157], v[192:195], v[102:105]
	v_mfma_f32_16x16x32_bf16 v[94:97], v[140:143], v[200:203], v[94:97]
	v_mfma_f32_16x16x32_bf16 v[86:89], v[154:157], v[200:203], v[86:89]
	v_mfma_f32_16x16x32_bf16 v[78:81], v[140:143], v[208:211], v[78:81]
	v_mfma_f32_16x16x32_bf16 v[70:73], v[154:157], v[208:211], v[70:73]
	v_mfma_f32_16x16x32_bf16 v[126:129], v[150:153], v[188:191], v[126:129]
	v_mfma_f32_16x16x32_bf16 v[118:121], v[158:161], v[188:191], v[118:121]
	v_mfma_f32_16x16x32_bf16 v[110:113], v[150:153], v[196:199], v[110:113]
	v_mfma_f32_16x16x32_bf16 v[102:105], v[158:161], v[196:199], v[102:105]
	v_mfma_f32_16x16x32_bf16 v[94:97], v[150:153], v[204:207], v[94:97]
	v_mfma_f32_16x16x32_bf16 v[86:89], v[158:161], v[204:207], v[86:89]
	v_mfma_f32_16x16x32_bf16 v[78:81], v[150:153], v[212:215], v[78:81]
	v_mfma_f32_16x16x32_bf16 v[70:73], v[158:161], v[212:215], v[70:73]
	v_mfma_f32_16x16x32_bf16 v[122:125], v[162:165], v[178:181], v[122:125]
	v_mfma_f32_16x16x32_bf16 v[114:117], v[170:173], v[178:181], v[114:117]
	v_mfma_f32_16x16x32_bf16 v[106:109], v[162:165], v[192:195], v[106:109]
	v_mfma_f32_16x16x32_bf16 v[98:101], v[170:173], v[192:195], v[98:101]
	v_mfma_f32_16x16x32_bf16 v[90:93], v[162:165], v[200:203], v[90:93]
	v_mfma_f32_16x16x32_bf16 v[82:85], v[170:173], v[200:203], v[82:85]
	v_mfma_f32_16x16x32_bf16 v[74:77], v[162:165], v[208:211], v[74:77]
	v_mfma_f32_16x16x32_bf16 v[66:69], v[170:173], v[208:211], v[66:69]
	v_mfma_f32_16x16x32_bf16 v[122:125], v[166:169], v[188:191], v[122:125]
	v_mfma_f32_16x16x32_bf16 v[114:117], v[174:177], v[188:191], v[114:117]
	v_mfma_f32_16x16x32_bf16 v[106:109], v[166:169], v[196:199], v[106:109]
	v_mfma_f32_16x16x32_bf16 v[98:101], v[174:177], v[196:199], v[98:101]
	v_mfma_f32_16x16x32_bf16 v[90:93], v[166:169], v[204:207], v[90:93]
	v_mfma_f32_16x16x32_bf16 v[82:85], v[174:177], v[204:207], v[82:85]
	v_mfma_f32_16x16x32_bf16 v[74:77], v[166:169], v[212:215], v[74:77]
	v_mfma_f32_16x16x32_bf16 v[66:69], v[174:177], v[212:215], v[66:69]
	s_barrier
	s_add_i32 s28, s46, s31
	v_lshl_add_u64 v[184:185], v[184:185], 0, s[74:75]
	s_mov_b32 m0, s28
	ds_read_b128 v[178:181], v148 offset:49152
	ds_read_b128 v[188:191], v148 offset:50176
	ds_read_b128 v[192:195], v148 offset:51200
	ds_read_b128 v[196:199], v148 offset:52224
	ds_read_b128 v[200:203], v148 offset:53248
	ds_read_b128 v[204:207], v148 offset:54272
	ds_read_b128 v[208:211], v148 offset:55296
	ds_read_b128 v[212:215], v148 offset:56320
	global_load_lds_dwordx4 v[184:185], off
	s_add_i32 m0, s28, 0x2000
	s_add_u32 s26, s26, 0x40080
	v_lshl_add_u64 v[184:185], v[186:187], 0, s[74:75]
	s_addc_u32 s27, s27, 0
	s_add_i32 s28, s47, s31
	global_load_lds_dwordx4 v[184:185], off
	v_lshl_add_u64 v[184:185], s[26:27], 0, v[0:1]
	s_mov_b32 m0, s28
	s_nop 0
	global_load_lds_dwordx4 v[184:185], off
	v_lshl_add_u64 v[184:185], s[26:27], 0, v[130:131]
	s_add_i32 m0, s28, 0x2000
	s_nop 0
	global_load_lds_dwordx4 v[184:185], off
	v_lshl_add_u64 v[184:185], v[216:217], 0, s[74:75]
	s_mov_b32 m0, s37
	s_nop 0
	global_load_lds_dwordx4 v[184:185], off
	v_lshl_add_u64 v[184:185], v[218:219], 0, s[74:75]
	s_mov_b32 m0, s38
	s_nop 0
	global_load_lds_dwordx4 v[184:185], off
	s_waitcnt vmcnt(8)
	s_waitcnt lgkmcnt(0)
	s_barrier
	s_waitcnt lgkmcnt(0)
	v_mfma_f32_16x16x32_bf16 v[62:65], v[140:143], v[178:181], v[62:65]
	v_mfma_f32_16x16x32_bf16 v[54:57], v[154:157], v[178:181], v[54:57]
	v_mfma_f32_16x16x32_bf16 v[46:49], v[140:143], v[192:195], v[46:49]
	v_mfma_f32_16x16x32_bf16 v[38:41], v[154:157], v[192:195], v[38:41]
	v_mfma_f32_16x16x32_bf16 v[30:33], v[140:143], v[200:203], v[30:33]
	v_mfma_f32_16x16x32_bf16 v[22:25], v[154:157], v[200:203], v[22:25]
	v_mfma_f32_16x16x32_bf16 v[14:17], v[140:143], v[208:211], v[14:17]
	v_mfma_f32_16x16x32_bf16 v[6:9], v[154:157], v[208:211], v[6:9]
	v_mfma_f32_16x16x32_bf16 v[62:65], v[150:153], v[188:191], v[62:65]
	v_mfma_f32_16x16x32_bf16 v[54:57], v[158:161], v[188:191], v[54:57]
	v_mfma_f32_16x16x32_bf16 v[46:49], v[150:153], v[196:199], v[46:49]
	v_mfma_f32_16x16x32_bf16 v[38:41], v[158:161], v[196:199], v[38:41]
	v_mfma_f32_16x16x32_bf16 v[30:33], v[150:153], v[204:207], v[30:33]
	v_mfma_f32_16x16x32_bf16 v[22:25], v[158:161], v[204:207], v[22:25]
	v_mfma_f32_16x16x32_bf16 v[14:17], v[150:153], v[212:215], v[14:17]
	v_mfma_f32_16x16x32_bf16 v[6:9], v[158:161], v[212:215], v[6:9]
	v_mfma_f32_16x16x32_bf16 v[58:61], v[162:165], v[178:181], v[58:61]
	v_mfma_f32_16x16x32_bf16 v[50:53], v[170:173], v[178:181], v[50:53]
	v_mfma_f32_16x16x32_bf16 v[42:45], v[162:165], v[192:195], v[42:45]
	v_mfma_f32_16x16x32_bf16 v[34:37], v[170:173], v[192:195], v[34:37]
	v_mfma_f32_16x16x32_bf16 v[26:29], v[162:165], v[200:203], v[26:29]
	v_mfma_f32_16x16x32_bf16 v[18:21], v[170:173], v[200:203], v[18:21]
	v_mfma_f32_16x16x32_bf16 v[10:13], v[162:165], v[208:211], v[10:13]
	v_mfma_f32_16x16x32_bf16 v[2:5], v[170:173], v[208:211], v[2:5]
	v_mfma_f32_16x16x32_bf16 v[58:61], v[166:169], v[188:191], v[58:61]
	v_mfma_f32_16x16x32_bf16 v[50:53], v[174:177], v[188:191], v[50:53]
	v_mfma_f32_16x16x32_bf16 v[42:45], v[166:169], v[196:199], v[42:45]
	v_mfma_f32_16x16x32_bf16 v[34:37], v[174:177], v[196:199], v[34:37]
	v_mfma_f32_16x16x32_bf16 v[26:29], v[166:169], v[204:207], v[26:29]
	v_mfma_f32_16x16x32_bf16 v[18:21], v[174:177], v[204:207], v[18:21]
	v_mfma_f32_16x16x32_bf16 v[10:13], v[166:169], v[212:215], v[10:13]
	v_mfma_f32_16x16x32_bf16 v[2:5], v[174:177], v[212:215], v[2:5]
	s_barrier
	s_add_i32 s44, s44, 2
	s_add_u32 s21, s21, 0x100
	s_addc_u32 s43, s43, 0
	s_add_u32 s24, s24, 0x100
	s_addc_u32 s25, s25, 0
	s_cmp_gt_u32 s44, 13
	s_cbranch_scc0 .LBB0_402
	s_and_b64 vcc, exec, s[18:19]
	s_cbranch_vccz .LBB0_405
	s_barrier

.LBB0_459:
	s_mov_b64 s[0:1], s[66:67]
	s_load_dwordx2 s[6:7], s[0:1], 0x100
	v_readlane_b32 s2, v255, 34
	v_readlane_b32 s3, v255, 35
	s_setprio 0
	s_getreg_b32 s0, hwreg(HW_REG_XCC_ID, 0, 4)
	v_mov_b32_e32 v0, v1
	s_and_b64 vcc, exec, s[2:3]
	s_mov_b64 s[8:9], 0
	s_cbranch_vccnz .LBB0_461
	v_mbcnt_lo_u32_b32 v0, -1, v0
	v_mbcnt_hi_u32_b32 v0, -1, v0
	v_cmp_eq_u32_e32 vcc, 0, v0
	s_and_b64 s[8:9], vcc, exec

.LBB0_514:
	s_or_b64 exec, exec, s[4:5]
	s_mov_b64 s[4:5], s[66:67]
	v_mov_b32_e32 v0, v1
	s_waitcnt lgkmcnt(0)
	s_barrier
	s_cmp_lt_u32 s86, 0x100
	s_cbranch_scc1 .Lprio_0
	s_setprio 1
.Lprio_0:
	v_readlane_b32 s0, v254, 27
	v_mbcnt_lo_u32_b32 v0, -1, v0
	v_mbcnt_hi_u32_b32 v18, -1, v0
	v_add_u32_e32 v0, s86, v18
	v_readlane_b32 s1, v254, 28
	s_andn2_b64 vcc, exec, s[0:1]
	v_readfirstlane_b32 s6, v0
	s_cbranch_vccnz .LBB0_538
	v_lshlrev_b32_e32 v2, 4, v0
	v_add_u32_e32 v3, 0x2000, v2
	v_ashrrev_i32_e32 v4, 31, v3
	v_lshrrev_b32_e32 v4, 22, v4
	v_add_u32_e32 v4, v3, v4
	v_ashrrev_i32_e32 v10, 10, v4
	v_mul_i32_i24_e32 v4, 0x400, v10
	v_sub_u32_e32 v3, v3, v4
	v_lshrrev_b32_e32 v4, 4, v3
	v_bitop3_b32 v3, v4, v3, 32 bitop3:0x6c
	v_ashrrev_i32_e32 v4, 31, v3
	v_lshrrev_b32_e32 v4, 26, v4
	v_add_u32_e32 v4, v3, v4
	v_lshlrev_b32_e32 v5, 3, v10
	v_ashrrev_i32_e32 v11, 6, v4
	v_and_b32_e32 v5, -16, v5
	v_add_u32_e32 v5, v11, v5
	v_and_b32_e32 v6, 3, v11
	s_mov_b32 s9, 0xffffe0
	v_lshrrev_b32_e32 v7, 2, v5
	v_lshlrev_b32_e32 v8, 1, v5
	v_and_b32_e32 v4, 0xc0, v4
	v_and_or_b32 v6, v5, s9, v6
	v_and_b32_e32 v7, 4, v7
	v_and_b32_e32 v8, 24, v8
	v_sub_u32_e32 v3, v3, v4
	v_or3_b32 v6, v6, v7, v8
	v_lshlrev_b32_e32 v7, 5, v10
	v_ashrrev_i16_sdwa v3, v236, sext(v3) dst_sel:DWORD dst_unused:UNUSED_PAD src0_sel:DWORD src1_sel:BYTE_0
	v_and_b32_e32 v12, 32, v7
	v_bfe_i32 v13, v3, 0, 16
	s_movk_i32 s8, 0xb00
	v_mul_u32_u24_e32 v6, 0xb00, v6
	v_add_u32_e32 v3, v12, v13
	v_mul_lo_u32 v4, v5, s8
	v_add_lshl_u32 v130, v6, v3, 1
	v_add_lshl_u32 v132, v3, v4, 1
	v_bfe_i32 v3, v0, 27, 1
	s_load_dwordx2 s[4:5], s[4:5], 0x100
	v_lshrrev_b32_e32 v3, 22, v3
	v_add_u32_e32 v3, v2, v3
	v_and_b32_e32 v3, 0xfffffc00, v3
	v_sub_u32_e32 v2, v2, v3
	v_lshrrev_b32_e32 v3, 4, v2
	v_ashrrev_i32_e32 v4, 31, v0
	s_waitcnt lgkmcnt(0)
	s_add_u32 s0, s4, 0x6c00000
	v_bitop3_b32 v2, v3, v2, 32 bitop3:0x6c
	v_lshrrev_b32_e32 v4, 26, v4
	s_mul_hi_u32 s2, s52, 0x580000
	s_mul_i32 s52, s52, 0x580000
	s_addc_u32 s1, s5, 0
	v_ashrrev_i32_e32 v3, 31, v2
	v_add_u32_e32 v0, v0, v4
	s_add_u32 s3, s4, s52
	v_lshrrev_b32_e32 v3, 26, v3
	v_ashrrev_i32_e32 v15, 6, v0
	s_addc_u32 s7, s5, s2
	v_add_u32_e32 v3, v2, v3
	v_lshlrev_b32_e32 v0, 3, v15
	s_add_u32 s2, s3, 0x2c00000
	v_ashrrev_i32_e32 v14, 6, v3
	v_and_b32_e32 v0, -16, v0
	s_addc_u32 s3, s7, 0
	s_ashr_i32 s7, s6, 6
	v_add_u32_e32 v4, v14, v0
	v_and_b32_e32 v3, 0xc0, v3
	s_ashr_i32 s10, s6, 8
	s_lshl_b32 s22, s7, 10
	v_and_b32_e32 v0, 3, v14
	v_lshrrev_b32_e32 v5, 2, v4
	v_lshlrev_b32_e32 v6, 1, v4
	v_sub_u32_e32 v2, v2, v3
	v_mul_lo_u32 v3, v4, s8
	v_readlane_b32 s8, v254, 39
	v_and_or_b32 v0, v4, s9, v0
	v_and_b32_e32 v5, 4, v5
	v_and_b32_e32 v6, 24, v6
	s_add_u32 s8, s2, s8
	v_readlane_b32 s9, v254, 38
	v_or3_b32 v0, v0, v5, v6
	v_lshlrev_b32_e32 v5, 5, v15
	v_ashrrev_i16_sdwa v2, v236, sext(v2) dst_sel:DWORD dst_unused:UNUSED_PAD src0_sel:DWORD src1_sel:BYTE_0
	s_addc_u32 s9, s3, s9
	v_readlane_b32 s14, v254, 37
	v_and_b32_e32 v16, 32, v5
	v_bfe_i32 v17, v2, 0, 16
	s_add_u32 s16, s8, s14
	v_readlane_b32 s13, v254, 36
	v_mul_u32_u24_e32 v0, 0xb00, v0
	v_add_u32_e32 v2, v16, v17
	s_addc_u32 s17, s9, s13
	s_add_i32 s23, s22, 0
	v_add_lshl_u32 v0, v0, v2, 1
	s_add_i32 m0, s23, 0x10000
	v_readlane_b32 s8, v254, 56
	global_load_lds_dwordx4 v0, s[16:17]
	s_add_i32 m0, s23, 0x12000
	s_mov_b32 s12, s8
	s_mul_i32 s8, s8, 0x160000
	s_add_u32 s11, s0, s8
	s_mul_hi_i32 s8, s12, 0x160000
	s_addc_u32 s12, s1, s8
	v_readlane_b32 s9, v254, 57
	s_add_u32 s8, s16, 0xb0000
	global_load_lds_dwordx4 v130, s[16:17]
	s_addc_u32 s9, s17, 0
	s_add_i32 m0, s23, 0x14000
	v_add_lshl_u32 v134, v2, v3, 1
	global_load_lds_dwordx4 v0, s[8:9]
	s_add_i32 m0, s23, 0x16000
	s_add_u32 s14, s11, s14
	s_addc_u32 s15, s12, s13
	s_add_i32 s24, s23, 0x2000
	global_load_lds_dwordx4 v130, s[8:9]
	s_mov_b32 m0, s23
	s_add_u32 s8, s14, 0xb0000
	global_load_lds_dwordx4 v134, s[14:15]
	s_mov_b32 m0, s24
	s_addc_u32 s9, s15, 0
	s_add_i32 s25, s23, 0x4000
	global_load_lds_dwordx4 v132, s[14:15]
	s_mov_b32 m0, s25
	s_add_i32 s26, s23, 0x6000
	global_load_lds_dwordx4 v134, s[8:9]
	s_mov_b32 m0, s26
	v_mov_b32_e32 v131, v1
	global_load_lds_dwordx4 v132, s[8:9]
	v_mov_b32_e32 v135, v1
	v_mov_b32_e32 v133, v1
	s_cmp_eq_u32 s10, 1
	v_lshl_add_u64 v[8:9], s[16:17], 0, v[0:1]
	v_lshl_add_u64 v[6:7], s[16:17], 0, v[130:131]
	v_lshl_add_u64 v[2:3], s[14:15], 0, v[134:135]
	s_cselect_b64 s[8:9], -1, 0
	s_cmp_lg_u32 s10, 1
	v_lshl_add_u64 v[4:5], s[14:15], 0, v[132:133]
	s_cbranch_scc1 .LBB0_517
	s_barrier

.LBB0_531:
	s_add_u32 s16, s14, 0x100
	s_addc_u32 s17, s15, 0
	s_add_i32 s40, 0, 0x10000
	s_cmp_eq_u32 s39, 18
	s_cselect_b32 s21, s7, s17
	s_cselect_b32 s20, s6, s16
	v_add_u32_e32 v140, s40, v143
	s_cselect_b32 s19, s13, s38
	s_cselect_b32 s18, s12, s37
	s_add_i32 s41, 0, 0x14000
	ds_read_b128 v[146:149], v140
	ds_read_b128 v[150:153], v140 offset:1024
	ds_read_b128 v[154:157], v140 offset:2048
	ds_read_b128 v[158:161], v140 offset:3072
	v_add_u32_e32 v140, s41, v143
	ds_read_b128 v[162:165], v140
	ds_read_b128 v[166:169], v140 offset:1024
	ds_read_b128 v[170:173], v140 offset:2048
	ds_read_b128 v[174:177], v140 offset:3072
	v_lshl_add_u64 v[140:141], s[14:15], 0, v[138:139]
	s_add_i32 m0, s23, 0xc000
	ds_read_b128 v[178:181], v145
	ds_read_b128 v[188:191], v145 offset:1024
	ds_read_b128 v[192:195], v145 offset:2048
	ds_read_b128 v[196:199], v145 offset:3072
	ds_read_b128 v[200:203], v145 offset:4096
	ds_read_b128 v[204:207], v145 offset:5120
	ds_read_b128 v[208:211], v145 offset:6144
	ds_read_b128 v[212:215], v145 offset:7168
	global_load_lds_dwordx4 v[140:141], off
	v_lshl_add_u64 v[140:141], s[14:15], 0, v[136:137]
	s_add_i32 m0, s23, 0xe000
	s_nop 0
	global_load_lds_dwordx4 v[140:141], off
	s_waitcnt vmcnt(8)
	s_waitcnt lgkmcnt(0)
	s_barrier
	s_waitcnt lgkmcnt(0)
	v_mfma_f32_16x16x32_bf16 v[126:129], v[146:149], v[178:181], v[126:129]
	v_mfma_f32_16x16x32_bf16 v[122:125], v[154:157], v[178:181], v[122:125]
	v_mfma_f32_16x16x32_bf16 v[118:121], v[146:149], v[192:195], v[118:121]
	v_mfma_f32_16x16x32_bf16 v[110:113], v[154:157], v[192:195], v[110:113]
	v_mfma_f32_16x16x32_bf16 v[102:105], v[146:149], v[200:203], v[102:105]
	v_mfma_f32_16x16x32_bf16 v[94:97], v[154:157], v[200:203], v[94:97]
	v_mfma_f32_16x16x32_bf16 v[86:89], v[146:149], v[208:211], v[86:89]
	v_mfma_f32_16x16x32_bf16 v[78:81], v[154:157], v[208:211], v[78:81]
	v_mfma_f32_16x16x32_bf16 v[126:129], v[150:153], v[188:191], v[126:129]
	v_mfma_f32_16x16x32_bf16 v[122:125], v[158:161], v[188:191], v[122:125]
	v_mfma_f32_16x16x32_bf16 v[118:121], v[150:153], v[196:199], v[118:121]
	v_mfma_f32_16x16x32_bf16 v[110:113], v[158:161], v[196:199], v[110:113]
	v_mfma_f32_16x16x32_bf16 v[102:105], v[150:153], v[204:207], v[102:105]
	v_mfma_f32_16x16x32_bf16 v[94:97], v[158:161], v[204:207], v[94:97]
	v_mfma_f32_16x16x32_bf16 v[86:89], v[150:153], v[212:215], v[86:89]
	v_mfma_f32_16x16x32_bf16 v[78:81], v[158:161], v[212:215], v[78:81]
	v_mfma_f32_16x16x32_bf16 v[114:117], v[162:165], v[178:181], v[114:117]
	v_mfma_f32_16x16x32_bf16 v[106:109], v[170:173], v[178:181], v[106:109]
	v_mfma_f32_16x16x32_bf16 v[98:101], v[162:165], v[192:195], v[98:101]
	v_mfma_f32_16x16x32_bf16 v[90:93], v[170:173], v[192:195], v[90:93]
	v_mfma_f32_16x16x32_bf16 v[82:85], v[162:165], v[200:203], v[82:85]
	v_mfma_f32_16x16x32_bf16 v[74:77], v[170:173], v[200:203], v[74:77]
	v_mfma_f32_16x16x32_bf16 v[70:73], v[162:165], v[208:211], v[70:73]
	v_mfma_f32_16x16x32_bf16 v[66:69], v[170:173], v[208:211], v[66:69]
	v_mfma_f32_16x16x32_bf16 v[114:117], v[166:169], v[188:191], v[114:117]
	v_mfma_f32_16x16x32_bf16 v[106:109], v[174:177], v[188:191], v[106:109]
	v_mfma_f32_16x16x32_bf16 v[98:101], v[166:169], v[196:199], v[98:101]
	v_mfma_f32_16x16x32_bf16 v[90:93], v[174:177], v[196:199], v[90:93]
	v_mfma_f32_16x16x32_bf16 v[82:85], v[166:169], v[204:207], v[82:85]
	v_mfma_f32_16x16x32_bf16 v[74:77], v[174:177], v[204:207], v[74:77]
	v_mfma_f32_16x16x32_bf16 v[70:73], v[166:169], v[212:215], v[70:73]
	v_mfma_f32_16x16x32_bf16 v[66:69], v[174:177], v[212:215], v[66:69]
	s_barrier
	s_add_i32 s14, s40, s22
	v_lshl_add_u64 v[140:141], s[18:19], 0, v[0:1]
	s_mov_b32 m0, s14
	ds_read_b128 v[178:181], v145 offset:16384
	ds_read_b128 v[188:191], v145 offset:17408
	ds_read_b128 v[192:195], v145 offset:18432
	ds_read_b128 v[196:199], v145 offset:19456
	ds_read_b128 v[200:203], v145 offset:20480
	ds_read_b128 v[204:207], v145 offset:21504
	ds_read_b128 v[208:211], v145 offset:22528
	ds_read_b128 v[212:215], v145 offset:23552
	global_load_lds_dwordx4 v[140:141], off
	s_add_i32 m0, s14, 0x2000
	s_add_u32 s14, s18, 0xb0000
	v_lshl_add_u64 v[184:185], s[18:19], 0, v[130:131]
	s_addc_u32 s15, s19, 0
	s_add_i32 s40, s41, s22
	global_load_lds_dwordx4 v[184:185], off
	v_lshl_add_u64 v[186:187], s[14:15], 0, v[0:1]
	s_mov_b32 m0, s40
	v_lshl_add_u64 v[216:217], s[20:21], 0, v[132:133]
	global_load_lds_dwordx4 v[186:187], off
	v_lshl_add_u64 v[186:187], s[14:15], 0, v[130:131]
	s_add_i32 m0, s40, 0x2000
	s_nop 0
	global_load_lds_dwordx4 v[186:187], off
	v_lshl_add_u64 v[186:187], s[20:21], 0, v[134:135]
	s_mov_b32 m0, s23
	s_nop 0
	global_load_lds_dwordx4 v[186:187], off
	s_mov_b32 m0, s24
	s_nop 0
	global_load_lds_dwordx4 v[216:217], off
	s_waitcnt vmcnt(8)
	s_waitcnt lgkmcnt(0)
	s_barrier
	s_waitcnt lgkmcnt(0)
	v_mfma_f32_16x16x32_bf16 v[62:65], v[146:149], v[178:181], v[62:65]
	v_mfma_f32_16x16x32_bf16 v[58:61], v[154:157], v[178:181], v[58:61]
	v_mfma_f32_16x16x32_bf16 v[54:57], v[146:149], v[192:195], v[54:57]
	v_mfma_f32_16x16x32_bf16 v[46:49], v[154:157], v[192:195], v[46:49]
	v_mfma_f32_16x16x32_bf16 v[38:41], v[146:149], v[200:203], v[38:41]
	v_mfma_f32_16x16x32_bf16 v[30:33], v[154:157], v[200:203], v[30:33]
	v_mfma_f32_16x16x32_bf16 v[22:25], v[146:149], v[208:211], v[22:25]
	v_mfma_f32_16x16x32_bf16 v[14:17], v[154:157], v[208:211], v[14:17]
	v_mfma_f32_16x16x32_bf16 v[62:65], v[150:153], v[188:191], v[62:65]
	v_mfma_f32_16x16x32_bf16 v[58:61], v[158:161], v[188:191], v[58:61]
	v_mfma_f32_16x16x32_bf16 v[54:57], v[150:153], v[196:199], v[54:57]
	v_mfma_f32_16x16x32_bf16 v[46:49], v[158:161], v[196:199], v[46:49]
	v_mfma_f32_16x16x32_bf16 v[38:41], v[150:153], v[204:207], v[38:41]
	v_mfma_f32_16x16x32_bf16 v[30:33], v[158:161], v[204:207], v[30:33]
	v_mfma_f32_16x16x32_bf16 v[22:25], v[150:153], v[212:215], v[22:25]
	v_mfma_f32_16x16x32_bf16 v[14:17], v[158:161], v[212:215], v[14:17]
	v_mfma_f32_16x16x32_bf16 v[50:53], v[162:165], v[178:181], v[50:53]
	v_mfma_f32_16x16x32_bf16 v[42:45], v[170:173], v[178:181], v[42:45]
	v_mfma_f32_16x16x32_bf16 v[34:37], v[162:165], v[192:195], v[34:37]
	v_mfma_f32_16x16x32_bf16 v[26:29], v[170:173], v[192:195], v[26:29]
	v_mfma_f32_16x16x32_bf16 v[18:21], v[162:165], v[200:203], v[18:21]
	v_mfma_f32_16x16x32_bf16 v[10:13], v[170:173], v[200:203], v[10:13]
	v_mfma_f32_16x16x32_bf16 v[6:9], v[162:165], v[208:211], v[6:9]
	v_mfma_f32_16x16x32_bf16 v[2:5], v[170:173], v[208:211], v[2:5]
	v_mfma_f32_16x16x32_bf16 v[50:53], v[166:169], v[188:191], v[50:53]
	v_mfma_f32_16x16x32_bf16 v[42:45], v[174:177], v[188:191], v[42:45]
	v_mfma_f32_16x16x32_bf16 v[34:37], v[166:169], v[196:199], v[34:37]
	v_mfma_f32_16x16x32_bf16 v[26:29], v[174:177], v[196:199], v[26:29]
	v_mfma_f32_16x16x32_bf16 v[18:21], v[166:169], v[204:207], v[18:21]
	v_mfma_f32_16x16x32_bf16 v[10:13], v[174:177], v[204:207], v[10:13]
	v_mfma_f32_16x16x32_bf16 v[6:9], v[166:169], v[212:215], v[6:9]
	v_mfma_f32_16x16x32_bf16 v[2:5], v[174:177], v[212:215], v[2:5]
	s_barrier
	s_add_i32 s40, 0, 0x18000
	s_add_i32 s41, 0, 0x1c000
	v_add_u32_e32 v158, s40, v143
	v_add_u32_e32 v174, s41, v143
	ds_read_b128 v[146:149], v158
	ds_read_b128 v[150:153], v158 offset:1024
	ds_read_b128 v[154:157], v158 offset:2048
	ds_read_b128 v[158:161], v158 offset:3072
	ds_read_b128 v[162:165], v174
	ds_read_b128 v[166:169], v174 offset:1024
	ds_read_b128 v[170:173], v174 offset:2048
	ds_read_b128 v[174:177], v174 offset:3072
	s_add_u32 s14, s20, 0xb0000
	s_addc_u32 s15, s21, 0
	s_mov_b32 m0, s25
	v_lshl_add_u64 v[218:219], s[14:15], 0, v[134:135]
	ds_read_b128 v[178:181], v145 offset:32768
	ds_read_b128 v[188:191], v145 offset:33792
	ds_read_b128 v[192:195], v145 offset:34816
	ds_read_b128 v[196:199], v145 offset:35840
	ds_read_b128 v[200:203], v145 offset:36864
	ds_read_b128 v[204:207], v145 offset:37888
	ds_read_b128 v[208:211], v145 offset:38912
	ds_read_b128 v[212:215], v145 offset:39936
	global_load_lds_dwordx4 v[218:219], off
	v_lshl_add_u64 v[218:219], s[14:15], 0, v[132:133]
	s_mov_b32 m0, s26
	s_nop 0
	global_load_lds_dwordx4 v[218:219], off
	s_waitcnt vmcnt(8)
	s_waitcnt lgkmcnt(0)
	s_barrier
	s_waitcnt lgkmcnt(0)
	v_mfma_f32_16x16x32_bf16 v[126:129], v[146:149], v[178:181], v[126:129]
	v_mfma_f32_16x16x32_bf16 v[122:125], v[154:157], v[178:181], v[122:125]
	v_mfma_f32_16x16x32_bf16 v[118:121], v[146:149], v[192:195], v[118:121]
	v_mfma_f32_16x16x32_bf16 v[110:113], v[154:157], v[192:195], v[110:113]
	v_mfma_f32_16x16x32_bf16 v[102:105], v[146:149], v[200:203], v[102:105]
	v_mfma_f32_16x16x32_bf16 v[94:97], v[154:157], v[200:203], v[94:97]
	v_mfma_f32_16x16x32_bf16 v[86:89], v[146:149], v[208:211], v[86:89]
	v_mfma_f32_16x16x32_bf16 v[78:81], v[154:157], v[208:211], v[78:81]
	v_mfma_f32_16x16x32_bf16 v[126:129], v[150:153], v[188:191], v[126:129]
	v_mfma_f32_16x16x32_bf16 v[122:125], v[158:161], v[188:191], v[122:125]
	v_mfma_f32_16x16x32_bf16 v[118:121], v[150:153], v[196:199], v[118:121]
	v_mfma_f32_16x16x32_bf16 v[110:113], v[158:161], v[196:199], v[110:113]
	v_mfma_f32_16x16x32_bf16 v[102:105], v[150:153], v[204:207], v[102:105]
	v_mfma_f32_16x16x32_bf16 v[94:97], v[158:161], v[204:207], v[94:97]
	v_mfma_f32_16x16x32_bf16 v[86:89], v[150:153], v[212:215], v[86:89]
	v_mfma_f32_16x16x32_bf16 v[78:81], v[158:161], v[212:215], v[78:81]
	v_mfma_f32_16x16x32_bf16 v[114:117], v[162:165], v[178:181], v[114:117]
	v_mfma_f32_16x16x32_bf16 v[106:109], v[170:173], v[178:181], v[106:109]
	v_mfma_f32_16x16x32_bf16 v[98:101], v[162:165], v[192:195], v[98:101]
	v_mfma_f32_16x16x32_bf16 v[90:93], v[170:173], v[192:195], v[90:93]
	v_mfma_f32_16x16x32_bf16 v[82:85], v[162:165], v[200:203], v[82:85]
	v_mfma_f32_16x16x32_bf16 v[74:77], v[170:173], v[200:203], v[74:77]
	v_mfma_f32_16x16x32_bf16 v[70:73], v[162:165], v[208:211], v[70:73]
	v_mfma_f32_16x16x32_bf16 v[66:69], v[170:173], v[208:211], v[66:69]
	v_mfma_f32_16x16x32_bf16 v[114:117], v[166:169], v[188:191], v[114:117]
	v_mfma_f32_16x16x32_bf16 v[106:109], v[174:177], v[188:191], v[106:109]
	v_mfma_f32_16x16x32_bf16 v[98:101], v[166:169], v[196:199], v[98:101]
	v_mfma_f32_16x16x32_bf16 v[90:93], v[174:177], v[196:199], v[90:93]
	v_mfma_f32_16x16x32_bf16 v[82:85], v[166:169], v[204:207], v[82:85]
	v_mfma_f32_16x16x32_bf16 v[74:77], v[174:177], v[204:207], v[74:77]
	v_mfma_f32_16x16x32_bf16 v[70:73], v[166:169], v[212:215], v[70:73]
	v_mfma_f32_16x16x32_bf16 v[66:69], v[174:177], v[212:215], v[66:69]
	s_barrier
	s_add_i32 s14, s40, s22
	v_lshl_add_u64 v[140:141], v[140:141], 0, s[74:75]
	s_mov_b32 m0, s14
	ds_read_b128 v[178:181], v145 offset:49152
	ds_read_b128 v[188:191], v145 offset:50176
	ds_read_b128 v[192:195], v145 offset:51200
	ds_read_b128 v[196:199], v145 offset:52224
	ds_read_b128 v[200:203], v145 offset:53248
	ds_read_b128 v[204:207], v145 offset:54272
	ds_read_b128 v[208:211], v145 offset:55296
	ds_read_b128 v[212:215], v145 offset:56320
	global_load_lds_dwordx4 v[140:141], off
	s_add_i32 m0, s14, 0x2000
	s_add_u32 s14, s18, 0xb0080
	v_lshl_add_u64 v[140:141], v[184:185], 0, s[74:75]
	s_addc_u32 s15, s19, 0
	s_add_i32 s18, s41, s22
	global_load_lds_dwordx4 v[140:141], off
	v_lshl_add_u64 v[140:141], s[14:15], 0, v[0:1]
	s_mov_b32 m0, s18
	s_nop 0
	global_load_lds_dwordx4 v[140:141], off
	v_lshl_add_u64 v[140:141], s[14:15], 0, v[130:131]
	s_add_i32 m0, s18, 0x2000
	s_nop 0
	global_load_lds_dwordx4 v[140:141], off
	v_lshl_add_u64 v[140:141], v[186:187], 0, s[74:75]
	s_mov_b32 m0, s29
	s_nop 0
	global_load_lds_dwordx4 v[140:141], off
	v_lshl_add_u64 v[140:141], v[216:217], 0, s[74:75]
	s_mov_b32 m0, s30
	s_nop 0
	global_load_lds_dwordx4 v[140:141], off
	s_waitcnt vmcnt(8)
	s_waitcnt lgkmcnt(0)
	s_barrier
	s_waitcnt lgkmcnt(0)
	v_mfma_f32_16x16x32_bf16 v[62:65], v[146:149], v[178:181], v[62:65]
	v_mfma_f32_16x16x32_bf16 v[58:61], v[154:157], v[178:181], v[58:61]
	v_mfma_f32_16x16x32_bf16 v[54:57], v[146:149], v[192:195], v[54:57]
	v_mfma_f32_16x16x32_bf16 v[46:49], v[154:157], v[192:195], v[46:49]
	v_mfma_f32_16x16x32_bf16 v[38:41], v[146:149], v[200:203], v[38:41]
	v_mfma_f32_16x16x32_bf16 v[30:33], v[154:157], v[200:203], v[30:33]
	v_mfma_f32_16x16x32_bf16 v[22:25], v[146:149], v[208:211], v[22:25]
	v_mfma_f32_16x16x32_bf16 v[14:17], v[154:157], v[208:211], v[14:17]
	v_mfma_f32_16x16x32_bf16 v[62:65], v[150:153], v[188:191], v[62:65]
	v_mfma_f32_16x16x32_bf16 v[58:61], v[158:161], v[188:191], v[58:61]
	v_mfma_f32_16x16x32_bf16 v[54:57], v[150:153], v[196:199], v[54:57]
	v_mfma_f32_16x16x32_bf16 v[46:49], v[158:161], v[196:199], v[46:49]
	v_mfma_f32_16x16x32_bf16 v[38:41], v[150:153], v[204:207], v[38:41]
	v_mfma_f32_16x16x32_bf16 v[30:33], v[158:161], v[204:207], v[30:33]
	v_mfma_f32_16x16x32_bf16 v[22:25], v[150:153], v[212:215], v[22:25]
	v_mfma_f32_16x16x32_bf16 v[14:17], v[158:161], v[212:215], v[14:17]
	v_mfma_f32_16x16x32_bf16 v[50:53], v[162:165], v[178:181], v[50:53]
	v_mfma_f32_16x16x32_bf16 v[42:45], v[170:173], v[178:181], v[42:45]
	v_mfma_f32_16x16x32_bf16 v[34:37], v[162:165], v[192:195], v[34:37]
	v_mfma_f32_16x16x32_bf16 v[26:29], v[170:173], v[192:195], v[26:29]
	v_mfma_f32_16x16x32_bf16 v[18:21], v[162:165], v[200:203], v[18:21]
	v_mfma_f32_16x16x32_bf16 v[10:13], v[170:173], v[200:203], v[10:13]
	v_mfma_f32_16x16x32_bf16 v[6:9], v[162:165], v[208:211], v[6:9]
	v_mfma_f32_16x16x32_bf16 v[2:5], v[170:173], v[208:211], v[2:5]
	v_mfma_f32_16x16x32_bf16 v[50:53], v[166:169], v[188:191], v[50:53]
	v_mfma_f32_16x16x32_bf16 v[42:45], v[174:177], v[188:191], v[42:45]
	v_mfma_f32_16x16x32_bf16 v[34:37], v[166:169], v[196:199], v[34:37]
	v_mfma_f32_16x16x32_bf16 v[26:29], v[174:177], v[196:199], v[26:29]
	v_mfma_f32_16x16x32_bf16 v[18:21], v[166:169], v[204:207], v[18:21]
	v_mfma_f32_16x16x32_bf16 v[10:13], v[174:177], v[204:207], v[10:13]
	v_mfma_f32_16x16x32_bf16 v[6:9], v[166:169], v[212:215], v[6:9]
	v_mfma_f32_16x16x32_bf16 v[2:5], v[174:177], v[212:215], v[2:5]
	s_barrier
	s_add_i32 s39, s39, 2
	s_add_u32 s37, s37, 0x100
	s_addc_u32 s38, s38, 0
	s_cmp_gt_u32 s39, 19
	s_mov_b64 s[14:15], s[16:17]
	s_cbranch_scc0 .LBB0_531
	s_and_b64 vcc, exec, s[10:11]
	s_cbranch_vccz .LBB0_534
	s_barrier

.LBB0_610:
	s_add_i32 s51, s26, 2
	s_add_u32 s27, s24, 0xfffc0080
	s_addc_u32 s28, s25, -1
	s_add_i32 s52, 0, 0x10000
	s_cmp_eq_u32 s44, s26
	s_cselect_b32 s29, s19, s28
	s_cselect_b32 s28, s18, s27
	v_add_u32_e32 v140, s52, v144
	s_cselect_b32 s27, s21, s50
	s_cselect_b32 s26, s20, s49
	s_add_i32 s54, 0, 0x14000
	ds_read_b128 v[148:151], v140
	ds_read_b128 v[152:155], v140 offset:1024
	ds_read_b128 v[156:159], v140 offset:2048
	ds_read_b128 v[160:163], v140 offset:3072
	v_add_u32_e32 v140, s54, v144
	ds_read_b128 v[164:167], v140
	ds_read_b128 v[168:171], v140 offset:1024
	ds_read_b128 v[172:175], v140 offset:2048
	ds_read_b128 v[176:179], v140 offset:3072
	v_lshl_add_u64 v[140:141], s[24:25], 0, v[138:139]
	s_add_i32 m0, s35, 0xc000
	ds_read_b128 v[188:191], v146
	ds_read_b128 v[192:195], v146 offset:1024
	ds_read_b128 v[196:199], v146 offset:2048
	ds_read_b128 v[200:203], v146 offset:3072
	ds_read_b128 v[204:207], v146 offset:4096
	ds_read_b128 v[208:211], v146 offset:5120
	ds_read_b128 v[212:215], v146 offset:6144
	ds_read_b128 v[216:219], v146 offset:7168
	global_load_lds_dwordx4 v[140:141], off
	v_lshl_add_u64 v[140:141], s[24:25], 0, v[136:137]
	s_add_i32 m0, s35, 0xe000
	s_nop 0
	global_load_lds_dwordx4 v[140:141], off
	s_waitcnt vmcnt(8)
	s_waitcnt lgkmcnt(0)
	s_barrier
	s_waitcnt lgkmcnt(0)
	v_mfma_f32_16x16x32_bf16 v[126:129], v[148:151], v[188:191], v[126:129]
	v_mfma_f32_16x16x32_bf16 v[122:125], v[156:159], v[188:191], v[122:125]
	v_mfma_f32_16x16x32_bf16 v[118:121], v[148:151], v[196:199], v[118:121]
	v_mfma_f32_16x16x32_bf16 v[110:113], v[156:159], v[196:199], v[110:113]
	v_mfma_f32_16x16x32_bf16 v[102:105], v[148:151], v[204:207], v[102:105]
	v_mfma_f32_16x16x32_bf16 v[94:97], v[156:159], v[204:207], v[94:97]
	v_mfma_f32_16x16x32_bf16 v[86:89], v[148:151], v[212:215], v[86:89]
	v_mfma_f32_16x16x32_bf16 v[78:81], v[156:159], v[212:215], v[78:81]
	v_mfma_f32_16x16x32_bf16 v[126:129], v[152:155], v[192:195], v[126:129]
	v_mfma_f32_16x16x32_bf16 v[122:125], v[160:163], v[192:195], v[122:125]
	v_mfma_f32_16x16x32_bf16 v[118:121], v[152:155], v[200:203], v[118:121]
	v_mfma_f32_16x16x32_bf16 v[110:113], v[160:163], v[200:203], v[110:113]
	v_mfma_f32_16x16x32_bf16 v[102:105], v[152:155], v[208:211], v[102:105]
	v_mfma_f32_16x16x32_bf16 v[94:97], v[160:163], v[208:211], v[94:97]
	v_mfma_f32_16x16x32_bf16 v[86:89], v[152:155], v[216:219], v[86:89]
	v_mfma_f32_16x16x32_bf16 v[78:81], v[160:163], v[216:219], v[78:81]
	v_mfma_f32_16x16x32_bf16 v[114:117], v[164:167], v[188:191], v[114:117]
	v_mfma_f32_16x16x32_bf16 v[106:109], v[172:175], v[188:191], v[106:109]
	v_mfma_f32_16x16x32_bf16 v[98:101], v[164:167], v[196:199], v[98:101]
	v_mfma_f32_16x16x32_bf16 v[90:93], v[172:175], v[196:199], v[90:93]
	v_mfma_f32_16x16x32_bf16 v[82:85], v[164:167], v[204:207], v[82:85]
	v_mfma_f32_16x16x32_bf16 v[74:77], v[172:175], v[204:207], v[74:77]
	v_mfma_f32_16x16x32_bf16 v[70:73], v[164:167], v[212:215], v[70:73]
	v_mfma_f32_16x16x32_bf16 v[66:69], v[172:175], v[212:215], v[66:69]
	v_mfma_f32_16x16x32_bf16 v[114:117], v[168:171], v[192:195], v[114:117]
	v_mfma_f32_16x16x32_bf16 v[106:109], v[176:179], v[192:195], v[106:109]
	v_mfma_f32_16x16x32_bf16 v[98:101], v[168:171], v[200:203], v[98:101]
	v_mfma_f32_16x16x32_bf16 v[90:93], v[176:179], v[200:203], v[90:93]
	v_mfma_f32_16x16x32_bf16 v[82:85], v[168:171], v[208:211], v[82:85]
	v_mfma_f32_16x16x32_bf16 v[74:77], v[176:179], v[208:211], v[74:77]
	v_mfma_f32_16x16x32_bf16 v[70:73], v[168:171], v[216:219], v[70:73]
	v_mfma_f32_16x16x32_bf16 v[66:69], v[176:179], v[216:219], v[66:69]
	s_barrier
	s_add_i32 s52, s52, s34
	v_lshl_add_u64 v[140:141], s[26:27], 0, v[0:1]
	s_mov_b32 m0, s52
	ds_read_b128 v[188:191], v146 offset:16384
	ds_read_b128 v[192:195], v146 offset:17408
	ds_read_b128 v[196:199], v146 offset:18432
	ds_read_b128 v[200:203], v146 offset:19456
	ds_read_b128 v[204:207], v146 offset:20480
	ds_read_b128 v[208:211], v146 offset:21504
	ds_read_b128 v[212:215], v146 offset:22528
	ds_read_b128 v[216:219], v146 offset:23552
	global_load_lds_dwordx4 v[140:141], off
	s_add_i32 m0, s52, 0x2000
	s_add_u32 s52, s26, 0x40000
	v_lshl_add_u64 v[180:181], s[26:27], 0, v[130:131]
	s_addc_u32 s53, s27, 0
	s_add_i32 s54, s54, s34
	global_load_lds_dwordx4 v[180:181], off
	v_lshl_add_u64 v[184:185], s[52:53], 0, v[0:1]
	s_mov_b32 m0, s54
	v_lshl_add_u64 v[186:187], s[28:29], 0, v[132:133]
	global_load_lds_dwordx4 v[184:185], off
	v_lshl_add_u64 v[184:185], s[52:53], 0, v[130:131]
	s_add_i32 m0, s54, 0x2000
	s_nop 0
	global_load_lds_dwordx4 v[184:185], off
	v_lshl_add_u64 v[184:185], s[28:29], 0, v[134:135]
	s_mov_b32 m0, s35
	s_nop 0
	global_load_lds_dwordx4 v[184:185], off
	s_mov_b32 m0, s36
	s_nop 0
	global_load_lds_dwordx4 v[186:187], off
	s_waitcnt vmcnt(8)
	s_waitcnt lgkmcnt(0)
	s_barrier
	s_waitcnt lgkmcnt(0)
	v_mfma_f32_16x16x32_bf16 v[62:65], v[148:151], v[188:191], v[62:65]
	v_mfma_f32_16x16x32_bf16 v[58:61], v[156:159], v[188:191], v[58:61]
	v_mfma_f32_16x16x32_bf16 v[54:57], v[148:151], v[196:199], v[54:57]
	v_mfma_f32_16x16x32_bf16 v[46:49], v[156:159], v[196:199], v[46:49]
	v_mfma_f32_16x16x32_bf16 v[38:41], v[148:151], v[204:207], v[38:41]
	v_mfma_f32_16x16x32_bf16 v[30:33], v[156:159], v[204:207], v[30:33]
	v_mfma_f32_16x16x32_bf16 v[22:25], v[148:151], v[212:215], v[22:25]
	v_mfma_f32_16x16x32_bf16 v[14:17], v[156:159], v[212:215], v[14:17]
	v_mfma_f32_16x16x32_bf16 v[62:65], v[152:155], v[192:195], v[62:65]
	v_mfma_f32_16x16x32_bf16 v[58:61], v[160:163], v[192:195], v[58:61]
	v_mfma_f32_16x16x32_bf16 v[54:57], v[152:155], v[200:203], v[54:57]
	v_mfma_f32_16x16x32_bf16 v[46:49], v[160:163], v[200:203], v[46:49]
	v_mfma_f32_16x16x32_bf16 v[38:41], v[152:155], v[208:211], v[38:41]
	v_mfma_f32_16x16x32_bf16 v[30:33], v[160:163], v[208:211], v[30:33]
	v_mfma_f32_16x16x32_bf16 v[22:25], v[152:155], v[216:219], v[22:25]
	v_mfma_f32_16x16x32_bf16 v[14:17], v[160:163], v[216:219], v[14:17]
	v_mfma_f32_16x16x32_bf16 v[50:53], v[164:167], v[188:191], v[50:53]
	v_mfma_f32_16x16x32_bf16 v[42:45], v[172:175], v[188:191], v[42:45]
	v_mfma_f32_16x16x32_bf16 v[34:37], v[164:167], v[196:199], v[34:37]
	v_mfma_f32_16x16x32_bf16 v[26:29], v[172:175], v[196:199], v[26:29]
	v_mfma_f32_16x16x32_bf16 v[18:21], v[164:167], v[204:207], v[18:21]
	v_mfma_f32_16x16x32_bf16 v[10:13], v[172:175], v[204:207], v[10:13]
	v_mfma_f32_16x16x32_bf16 v[6:9], v[164:167], v[212:215], v[6:9]
	v_mfma_f32_16x16x32_bf16 v[2:5], v[172:175], v[212:215], v[2:5]
	v_mfma_f32_16x16x32_bf16 v[50:53], v[168:171], v[192:195], v[50:53]
	v_mfma_f32_16x16x32_bf16 v[42:45], v[176:179], v[192:195], v[42:45]
	v_mfma_f32_16x16x32_bf16 v[34:37], v[168:171], v[200:203], v[34:37]
	v_mfma_f32_16x16x32_bf16 v[26:29], v[176:179], v[200:203], v[26:29]
	v_mfma_f32_16x16x32_bf16 v[18:21], v[168:171], v[208:211], v[18:21]
	v_mfma_f32_16x16x32_bf16 v[10:13], v[176:179], v[208:211], v[10:13]
	v_mfma_f32_16x16x32_bf16 v[6:9], v[168:171], v[216:219], v[6:9]
	v_mfma_f32_16x16x32_bf16 v[2:5], v[176:179], v[216:219], v[2:5]
	s_barrier
	s_add_i32 s52, 0, 0x18000
	v_add_u32_e32 v147, s52, v144
	s_add_i32 s53, 0, 0x1c000
	ds_read_b128 v[148:151], v147
	ds_read_b128 v[152:155], v147 offset:1024
	ds_read_b128 v[156:159], v147 offset:2048
	ds_read_b128 v[160:163], v147 offset:3072
	v_add_u32_e32 v147, s53, v144
	ds_read_b128 v[164:167], v147
	ds_read_b128 v[168:171], v147 offset:1024
	ds_read_b128 v[172:175], v147 offset:2048
	ds_read_b128 v[176:179], v147 offset:3072
	s_add_u32 s28, s28, 0x40000
	s_addc_u32 s29, s29, 0
	s_mov_b32 m0, s37
	v_lshl_add_u64 v[220:221], s[28:29], 0, v[134:135]
	ds_read_b128 v[188:191], v146 offset:32768
	ds_read_b128 v[192:195], v146 offset:33792
	ds_read_b128 v[196:199], v146 offset:34816
	ds_read_b128 v[200:203], v146 offset:35840
	ds_read_b128 v[204:207], v146 offset:36864
	ds_read_b128 v[208:211], v146 offset:37888
	ds_read_b128 v[212:215], v146 offset:38912
	ds_read_b128 v[216:219], v146 offset:39936
	global_load_lds_dwordx4 v[220:221], off
	v_lshl_add_u64 v[220:221], s[28:29], 0, v[132:133]
	s_mov_b32 m0, s38
	s_nop 0
	global_load_lds_dwordx4 v[220:221], off
	s_waitcnt vmcnt(8)
	s_waitcnt lgkmcnt(0)
	s_barrier
	s_waitcnt lgkmcnt(0)
	v_mfma_f32_16x16x32_bf16 v[126:129], v[148:151], v[188:191], v[126:129]
	v_mfma_f32_16x16x32_bf16 v[122:125], v[156:159], v[188:191], v[122:125]
	v_mfma_f32_16x16x32_bf16 v[118:121], v[148:151], v[196:199], v[118:121]
	v_mfma_f32_16x16x32_bf16 v[110:113], v[156:159], v[196:199], v[110:113]
	v_mfma_f32_16x16x32_bf16 v[102:105], v[148:151], v[204:207], v[102:105]
	v_mfma_f32_16x16x32_bf16 v[94:97], v[156:159], v[204:207], v[94:97]
	v_mfma_f32_16x16x32_bf16 v[86:89], v[148:151], v[212:215], v[86:89]
	v_mfma_f32_16x16x32_bf16 v[78:81], v[156:159], v[212:215], v[78:81]
	v_mfma_f32_16x16x32_bf16 v[126:129], v[152:155], v[192:195], v[126:129]
	v_mfma_f32_16x16x32_bf16 v[122:125], v[160:163], v[192:195], v[122:125]
	v_mfma_f32_16x16x32_bf16 v[118:121], v[152:155], v[200:203], v[118:121]
	v_mfma_f32_16x16x32_bf16 v[110:113], v[160:163], v[200:203], v[110:113]
	v_mfma_f32_16x16x32_bf16 v[102:105], v[152:155], v[208:211], v[102:105]
	v_mfma_f32_16x16x32_bf16 v[94:97], v[160:163], v[208:211], v[94:97]
	v_mfma_f32_16x16x32_bf16 v[86:89], v[152:155], v[216:219], v[86:89]
	v_mfma_f32_16x16x32_bf16 v[78:81], v[160:163], v[216:219], v[78:81]
	v_mfma_f32_16x16x32_bf16 v[114:117], v[164:167], v[188:191], v[114:117]
	v_mfma_f32_16x16x32_bf16 v[106:109], v[172:175], v[188:191], v[106:109]
	v_mfma_f32_16x16x32_bf16 v[98:101], v[164:167], v[196:199], v[98:101]
	v_mfma_f32_16x16x32_bf16 v[90:93], v[172:175], v[196:199], v[90:93]
	v_mfma_f32_16x16x32_bf16 v[82:85], v[164:167], v[204:207], v[82:85]
	v_mfma_f32_16x16x32_bf16 v[74:77], v[172:175], v[204:207], v[74:77]
	v_mfma_f32_16x16x32_bf16 v[70:73], v[164:167], v[212:215], v[70:73]
	v_mfma_f32_16x16x32_bf16 v[66:69], v[172:175], v[212:215], v[66:69]
	v_mfma_f32_16x16x32_bf16 v[114:117], v[168:171], v[192:195], v[114:117]
	v_mfma_f32_16x16x32_bf16 v[106:109], v[176:179], v[192:195], v[106:109]
	v_mfma_f32_16x16x32_bf16 v[98:101], v[168:171], v[200:203], v[98:101]
	v_mfma_f32_16x16x32_bf16 v[90:93], v[176:179], v[200:203], v[90:93]
	v_mfma_f32_16x16x32_bf16 v[82:85], v[168:171], v[208:211], v[82:85]
	v_mfma_f32_16x16x32_bf16 v[74:77], v[176:179], v[208:211], v[74:77]
	v_mfma_f32_16x16x32_bf16 v[70:73], v[168:171], v[216:219], v[70:73]
	v_mfma_f32_16x16x32_bf16 v[66:69], v[176:179], v[216:219], v[66:69]
	s_barrier
	s_add_i32 s28, s52, s34
	v_lshl_add_u64 v[140:141], v[140:141], 0, s[74:75]
	s_mov_b32 m0, s28
	ds_read_b128 v[188:191], v146 offset:49152
	ds_read_b128 v[192:195], v146 offset:50176
	ds_read_b128 v[196:199], v146 offset:51200
	ds_read_b128 v[200:203], v146 offset:52224
	ds_read_b128 v[204:207], v146 offset:53248
	ds_read_b128 v[208:211], v146 offset:54272
	ds_read_b128 v[212:215], v146 offset:55296
	ds_read_b128 v[216:219], v146 offset:56320
	global_load_lds_dwordx4 v[140:141], off
	s_add_i32 m0, s28, 0x2000
	s_add_u32 s26, s26, 0x40080
	v_lshl_add_u64 v[140:141], v[180:181], 0, s[74:75]
	s_addc_u32 s27, s27, 0
	s_add_i32 s28, s53, s34
	global_load_lds_dwordx4 v[140:141], off
	v_lshl_add_u64 v[140:141], s[26:27], 0, v[0:1]
	s_mov_b32 m0, s28
	s_nop 0
	global_load_lds_dwordx4 v[140:141], off
	v_lshl_add_u64 v[140:141], s[26:27], 0, v[130:131]
	s_add_i32 m0, s28, 0x2000
	s_nop 0
	global_load_lds_dwordx4 v[140:141], off
	v_lshl_add_u64 v[140:141], v[184:185], 0, s[74:75]
	s_mov_b32 m0, s41
	s_nop 0
	global_load_lds_dwordx4 v[140:141], off
	v_lshl_add_u64 v[140:141], v[186:187], 0, s[74:75]
	s_mov_b32 m0, s42
	s_nop 0
	global_load_lds_dwordx4 v[140:141], off
	s_waitcnt vmcnt(8)
	s_waitcnt lgkmcnt(0)
	s_barrier
	s_waitcnt lgkmcnt(0)
	v_mfma_f32_16x16x32_bf16 v[62:65], v[148:151], v[188:191], v[62:65]
	v_mfma_f32_16x16x32_bf16 v[58:61], v[156:159], v[188:191], v[58:61]
	v_mfma_f32_16x16x32_bf16 v[54:57], v[148:151], v[196:199], v[54:57]
	v_mfma_f32_16x16x32_bf16 v[46:49], v[156:159], v[196:199], v[46:49]
	v_mfma_f32_16x16x32_bf16 v[38:41], v[148:151], v[204:207], v[38:41]
	v_mfma_f32_16x16x32_bf16 v[30:33], v[156:159], v[204:207], v[30:33]
	v_mfma_f32_16x16x32_bf16 v[22:25], v[148:151], v[212:215], v[22:25]
	v_mfma_f32_16x16x32_bf16 v[14:17], v[156:159], v[212:215], v[14:17]
	v_mfma_f32_16x16x32_bf16 v[62:65], v[152:155], v[192:195], v[62:65]
	v_mfma_f32_16x16x32_bf16 v[58:61], v[160:163], v[192:195], v[58:61]
	v_mfma_f32_16x16x32_bf16 v[54:57], v[152:155], v[200:203], v[54:57]
	v_mfma_f32_16x16x32_bf16 v[46:49], v[160:163], v[200:203], v[46:49]
	v_mfma_f32_16x16x32_bf16 v[38:41], v[152:155], v[208:211], v[38:41]
	v_mfma_f32_16x16x32_bf16 v[30:33], v[160:163], v[208:211], v[30:33]
	v_mfma_f32_16x16x32_bf16 v[22:25], v[152:155], v[216:219], v[22:25]
	v_mfma_f32_16x16x32_bf16 v[14:17], v[160:163], v[216:219], v[14:17]
	v_mfma_f32_16x16x32_bf16 v[50:53], v[164:167], v[188:191], v[50:53]
	v_mfma_f32_16x16x32_bf16 v[42:45], v[172:175], v[188:191], v[42:45]
	v_mfma_f32_16x16x32_bf16 v[34:37], v[164:167], v[196:199], v[34:37]
	v_mfma_f32_16x16x32_bf16 v[26:29], v[172:175], v[196:199], v[26:29]
	v_mfma_f32_16x16x32_bf16 v[18:21], v[164:167], v[204:207], v[18:21]
	v_mfma_f32_16x16x32_bf16 v[10:13], v[172:175], v[204:207], v[10:13]
	v_mfma_f32_16x16x32_bf16 v[6:9], v[164:167], v[212:215], v[6:9]
	v_mfma_f32_16x16x32_bf16 v[2:5], v[172:175], v[212:215], v[2:5]
	v_mfma_f32_16x16x32_bf16 v[50:53], v[168:171], v[192:195], v[50:53]
	v_mfma_f32_16x16x32_bf16 v[42:45], v[176:179], v[192:195], v[42:45]
	v_mfma_f32_16x16x32_bf16 v[34:37], v[168:171], v[200:203], v[34:37]
	v_mfma_f32_16x16x32_bf16 v[26:29], v[176:179], v[200:203], v[26:29]
	v_mfma_f32_16x16x32_bf16 v[18:21], v[168:171], v[208:211], v[18:21]
	v_mfma_f32_16x16x32_bf16 v[10:13], v[176:179], v[208:211], v[10:13]
	v_mfma_f32_16x16x32_bf16 v[6:9], v[168:171], v[216:219], v[6:9]
	v_mfma_f32_16x16x32_bf16 v[2:5], v[176:179], v[216:219], v[2:5]
	s_barrier
	s_add_u32 s49, s49, 0x100
	s_addc_u32 s50, s50, 0
	s_add_u32 s24, s24, 0x100
	s_addc_u32 s25, s25, 0
	s_cmp_ge_u32 s51, s17
	s_mov_b32 s26, s51
	s_cbranch_scc0 .LBB0_610
	s_and_b64 vcc, exec, s[14:15]
	s_cbranch_vccz .LBB0_613
	s_barrier

.LBB0_1310:
	s_or_b64 exec, exec, s[6:7]
	s_mov_b64 s[6:7], s[66:67]
	v_mov_b32_e32 v0, v1
	s_waitcnt lgkmcnt(0)
	s_barrier
	s_cmp_lt_u32 s86, 0x100
	s_cbranch_scc1 .Lprio_1
	s_setprio 1
.Lprio_1:
	s_and_b64 vcc, exec, s[4:5]
	v_mbcnt_lo_u32_b32 v0, -1, v0
	v_mbcnt_hi_u32_b32 v16, -1, v0
	v_add_u32_e32 v0, s86, v16
	s_nop 0
	v_readfirstlane_b32 s10, v0
	s_cbranch_vccnz .LBB0_1334
	v_lshlrev_b32_e32 v2, 4, v0
	v_add_u32_e32 v3, 0x2000, v2
	v_ashrrev_i32_e32 v4, 31, v3
	v_lshrrev_b32_e32 v4, 22, v4
	v_add_u32_e32 v4, v3, v4
	v_ashrrev_i32_e32 v10, 10, v4
	v_mul_i32_i24_e32 v4, 0x400, v10
	v_sub_u32_e32 v3, v3, v4
	v_lshrrev_b32_e32 v4, 4, v3
	v_bitop3_b32 v3, v4, v3, 32 bitop3:0x6c
	v_ashrrev_i32_e32 v4, 31, v3
	v_lshrrev_b32_e32 v4, 26, v4
	v_add_u32_e32 v4, v3, v4
	v_lshlrev_b32_e32 v5, 3, v10
	v_ashrrev_i32_e32 v11, 6, v4
	v_and_b32_e32 v5, -16, v5
	v_add_u32_e32 v5, v11, v5
	v_and_b32_e32 v6, 3, v11
	s_mov_b32 s8, 0x1fffe0
	v_lshrrev_b32_e32 v7, 2, v5
	v_lshlrev_b32_e32 v8, 1, v5
	v_and_b32_e32 v4, 0xc0, v4
	v_and_or_b32 v6, v5, s8, v6
	v_and_b32_e32 v7, 4, v7
	v_and_b32_e32 v8, 24, v8
	v_sub_u32_e32 v3, v3, v4
	v_or3_b32 v6, v6, v7, v8
	v_lshlrev_b32_e32 v7, 5, v10
	v_ashrrev_i16_sdwa v3, v236, sext(v3) dst_sel:DWORD dst_unused:UNUSED_PAD src0_sel:DWORD src1_sel:BYTE_0
	v_and_b32_e32 v7, 32, v7
	v_bfe_i32 v12, v3, 0, 16
	v_add_lshl_u32 v3, v7, v12, 1
	v_lshl_add_u32 v130, v6, 11, v3
	v_lshl_add_u32 v132, v5, 11, v3
	v_bfe_i32 v3, v0, 27, 1
	s_load_dwordx2 s[4:5], s[6:7], 0x100
	v_lshrrev_b32_e32 v3, 22, v3
	v_add_u32_e32 v3, v2, v3
	v_and_b32_e32 v3, 0xfffffc00, v3
	v_sub_u32_e32 v2, v2, v3
	v_lshrrev_b32_e32 v3, 4, v2
	v_ashrrev_i32_e32 v4, 31, v0
	s_waitcnt lgkmcnt(0)
	s_add_u32 s0, s4, 0xd800000
	v_bitop3_b32 v2, v3, v2, 32 bitop3:0x6c
	v_lshrrev_b32_e32 v4, 26, v4
	s_addc_u32 s1, s5, 0
	v_readlane_b32 s2, v255, 32
	v_ashrrev_i32_e32 v3, 31, v2
	v_add_u32_e32 v0, v0, v4
	s_add_u32 s2, s4, s2
	v_lshrrev_b32_e32 v3, 26, v3
	v_ashrrev_i32_e32 v14, 6, v0
	s_addc_u32 s3, s5, 0
	v_add_u32_e32 v3, v2, v3
	v_lshlrev_b32_e32 v0, 3, v14
	s_add_u32 s2, s2, 0x4c00000
	v_ashrrev_i32_e32 v13, 6, v3
	v_and_b32_e32 v0, -16, v0
	s_addc_u32 s3, s3, 0
	s_ashr_i32 s6, s10, 6
	v_add_u32_e32 v4, v13, v0
	v_and_b32_e32 v0, 3, v13
	s_ashr_i32 s7, s10, 8
	s_lshl_b32 s22, s6, 10
	v_and_or_b32 v0, v4, s8, v0
	v_lshrrev_b32_e32 v5, 2, v4
	v_lshlrev_b32_e32 v6, 1, v4
	v_and_b32_e32 v3, 0xc0, v3
	v_readlane_b32 s8, v254, 43
	v_and_b32_e32 v5, 4, v5
	v_and_b32_e32 v6, 24, v6
	v_sub_u32_e32 v2, v2, v3
	v_readlane_b32 s9, v254, 44
	s_add_u32 s8, s2, s8
	v_or3_b32 v0, v0, v5, v6
	v_lshlrev_b32_e32 v5, 5, v14
	v_ashrrev_i16_sdwa v2, v236, sext(v2) dst_sel:DWORD dst_unused:UNUSED_PAD src0_sel:DWORD src1_sel:BYTE_0
	s_addc_u32 s9, s3, s9
	v_readlane_b32 s14, v254, 41
	v_and_b32_e32 v5, 32, v5
	v_bfe_i32 v15, v2, 0, 16
	v_readlane_b32 s15, v254, 42
	s_add_u32 s16, s8, s14
	v_add_lshl_u32 v2, v5, v15, 1
	s_addc_u32 s17, s9, s15
	s_add_i32 s23, s22, 0
	v_lshl_add_u32 v0, v0, 11, v2
	s_add_i32 m0, s23, 0x10000
	v_readlane_b32 s8, v254, 58
	global_load_lds_dwordx4 v0, s[16:17]
	s_add_i32 m0, s23, 0x12000
	v_readlane_b32 s9, v254, 59
	s_add_u32 s11, s0, s8
	s_addc_u32 s12, s1, s9
	s_add_u32 s8, s16, 0x40000
	global_load_lds_dwordx4 v130, s[16:17]
	s_addc_u32 s9, s17, 0
	s_add_i32 m0, s23, 0x14000
	v_lshl_add_u32 v134, v4, 11, v2
	global_load_lds_dwordx4 v0, s[8:9]
	s_add_i32 m0, s23, 0x16000
	s_add_u32 s18, s11, s14
	s_addc_u32 s19, s12, s15
	s_add_i32 s24, s23, 0x2000
	global_load_lds_dwordx4 v130, s[8:9]
	s_mov_b32 m0, s23
	s_add_u32 s8, s18, 0x40000
	global_load_lds_dwordx4 v134, s[18:19]
	s_mov_b32 m0, s24
	s_addc_u32 s9, s19, 0
	s_add_i32 s25, s23, 0x4000
	global_load_lds_dwordx4 v132, s[18:19]
	s_mov_b32 m0, s25
	s_add_i32 s26, s23, 0x6000
	global_load_lds_dwordx4 v134, s[8:9]
	s_mov_b32 m0, s26
	v_mov_b32_e32 v131, v1
	global_load_lds_dwordx4 v132, s[8:9]
	v_mov_b32_e32 v135, v1
	v_mov_b32_e32 v133, v1
	s_cmp_eq_u32 s7, 1
	v_lshl_add_u64 v[8:9], s[16:17], 0, v[0:1]
	v_lshl_add_u64 v[6:7], s[16:17], 0, v[130:131]
	v_lshl_add_u64 v[2:3], s[18:19], 0, v[134:135]
	s_cselect_b64 s[8:9], -1, 0
	s_cmp_lg_u32 s7, 1
	v_lshl_add_u64 v[4:5], s[18:19], 0, v[132:133]
	s_cbranch_scc1 .LBB0_1313
	s_barrier

.LBB0_1327:
	s_add_u32 s18, s16, 0xfffc0080
	s_addc_u32 s19, s17, -1
	s_add_i32 s38, 0, 0x10000
	s_cmp_eq_u32 s37, 4
	s_cselect_b32 s21, s7, s19
	s_cselect_b32 s20, s6, s18
	v_add_u32_e32 v140, s38, v143
	s_cselect_b32 s19, s15, s36
	s_cselect_b32 s18, s14, s13
	s_add_i32 s40, 0, 0x14000
	ds_read_b128 v[146:149], v140
	ds_read_b128 v[150:153], v140 offset:1024
	ds_read_b128 v[154:157], v140 offset:2048
	ds_read_b128 v[158:161], v140 offset:3072
	v_add_u32_e32 v140, s40, v143
	ds_read_b128 v[162:165], v140
	ds_read_b128 v[166:169], v140 offset:1024
	ds_read_b128 v[170:173], v140 offset:2048
	ds_read_b128 v[174:177], v140 offset:3072
	v_lshl_add_u64 v[140:141], s[16:17], 0, v[138:139]
	s_add_i32 m0, s23, 0xc000
	ds_read_b128 v[178:181], v145
	ds_read_b128 v[184:187], v145 offset:1024
	ds_read_b128 v[188:191], v145 offset:2048
	ds_read_b128 v[192:195], v145 offset:3072
	ds_read_b128 v[196:199], v145 offset:4096
	ds_read_b128 v[200:203], v145 offset:5120
	ds_read_b128 v[204:207], v145 offset:6144
	ds_read_b128 v[208:211], v145 offset:7168
	global_load_lds_dwordx4 v[140:141], off
	v_lshl_add_u64 v[140:141], s[16:17], 0, v[136:137]
	s_add_i32 m0, s23, 0xe000
	s_nop 0
	global_load_lds_dwordx4 v[140:141], off
	s_waitcnt vmcnt(8)
	s_waitcnt lgkmcnt(0)
	s_barrier
	s_waitcnt lgkmcnt(0)
	v_mfma_f32_16x16x32_bf16 v[126:129], v[146:149], v[178:181], v[126:129]
	v_mfma_f32_16x16x32_bf16 v[122:125], v[154:157], v[178:181], v[122:125]
	v_mfma_f32_16x16x32_bf16 v[118:121], v[146:149], v[188:191], v[118:121]
	v_mfma_f32_16x16x32_bf16 v[110:113], v[154:157], v[188:191], v[110:113]
	v_mfma_f32_16x16x32_bf16 v[102:105], v[146:149], v[196:199], v[102:105]
	v_mfma_f32_16x16x32_bf16 v[94:97], v[154:157], v[196:199], v[94:97]
	v_mfma_f32_16x16x32_bf16 v[86:89], v[146:149], v[204:207], v[86:89]
	v_mfma_f32_16x16x32_bf16 v[78:81], v[154:157], v[204:207], v[78:81]
	v_mfma_f32_16x16x32_bf16 v[126:129], v[150:153], v[184:187], v[126:129]
	v_mfma_f32_16x16x32_bf16 v[122:125], v[158:161], v[184:187], v[122:125]
	v_mfma_f32_16x16x32_bf16 v[118:121], v[150:153], v[192:195], v[118:121]
	v_mfma_f32_16x16x32_bf16 v[110:113], v[158:161], v[192:195], v[110:113]
	v_mfma_f32_16x16x32_bf16 v[102:105], v[150:153], v[200:203], v[102:105]
	v_mfma_f32_16x16x32_bf16 v[94:97], v[158:161], v[200:203], v[94:97]
	v_mfma_f32_16x16x32_bf16 v[86:89], v[150:153], v[208:211], v[86:89]
	v_mfma_f32_16x16x32_bf16 v[78:81], v[158:161], v[208:211], v[78:81]
	v_mfma_f32_16x16x32_bf16 v[114:117], v[162:165], v[178:181], v[114:117]
	v_mfma_f32_16x16x32_bf16 v[106:109], v[170:173], v[178:181], v[106:109]
	v_mfma_f32_16x16x32_bf16 v[98:101], v[162:165], v[188:191], v[98:101]
	v_mfma_f32_16x16x32_bf16 v[90:93], v[170:173], v[188:191], v[90:93]
	v_mfma_f32_16x16x32_bf16 v[82:85], v[162:165], v[196:199], v[82:85]
	v_mfma_f32_16x16x32_bf16 v[74:77], v[170:173], v[196:199], v[74:77]
	v_mfma_f32_16x16x32_bf16 v[70:73], v[162:165], v[204:207], v[70:73]
	v_mfma_f32_16x16x32_bf16 v[66:69], v[170:173], v[204:207], v[66:69]
	v_mfma_f32_16x16x32_bf16 v[114:117], v[166:169], v[184:187], v[114:117]
	v_mfma_f32_16x16x32_bf16 v[106:109], v[174:177], v[184:187], v[106:109]
	v_mfma_f32_16x16x32_bf16 v[98:101], v[166:169], v[192:195], v[98:101]
	v_mfma_f32_16x16x32_bf16 v[90:93], v[174:177], v[192:195], v[90:93]
	v_mfma_f32_16x16x32_bf16 v[82:85], v[166:169], v[200:203], v[82:85]
	v_mfma_f32_16x16x32_bf16 v[74:77], v[174:177], v[200:203], v[74:77]
	v_mfma_f32_16x16x32_bf16 v[70:73], v[166:169], v[208:211], v[70:73]
	v_mfma_f32_16x16x32_bf16 v[66:69], v[174:177], v[208:211], v[66:69]
	s_barrier
	s_add_i32 s38, s38, s22
	v_lshl_add_u64 v[140:141], s[18:19], 0, v[0:1]
	s_mov_b32 m0, s38
	ds_read_b128 v[178:181], v145 offset:16384
	ds_read_b128 v[184:187], v145 offset:17408
	ds_read_b128 v[188:191], v145 offset:18432
	ds_read_b128 v[192:195], v145 offset:19456
	ds_read_b128 v[196:199], v145 offset:20480
	ds_read_b128 v[200:203], v145 offset:21504
	ds_read_b128 v[204:207], v145 offset:22528
	ds_read_b128 v[208:211], v145 offset:23552
	global_load_lds_dwordx4 v[140:141], off
	s_add_i32 m0, s38, 0x2000
	s_add_u32 s38, s18, 0x40000
	v_lshl_add_u64 v[212:213], s[18:19], 0, v[130:131]
	s_addc_u32 s39, s19, 0
	s_add_i32 s40, s40, s22
	global_load_lds_dwordx4 v[212:213], off
	v_lshl_add_u64 v[214:215], s[38:39], 0, v[0:1]
	s_mov_b32 m0, s40
	v_lshl_add_u64 v[216:217], s[20:21], 0, v[132:133]
	global_load_lds_dwordx4 v[214:215], off
	v_lshl_add_u64 v[214:215], s[38:39], 0, v[130:131]
	s_add_i32 m0, s40, 0x2000
	s_nop 0
	global_load_lds_dwordx4 v[214:215], off
	v_lshl_add_u64 v[214:215], s[20:21], 0, v[134:135]
	s_mov_b32 m0, s23
	s_nop 0
	global_load_lds_dwordx4 v[214:215], off
	s_mov_b32 m0, s24
	s_nop 0
	global_load_lds_dwordx4 v[216:217], off
	s_waitcnt vmcnt(8)
	s_waitcnt lgkmcnt(0)
	s_barrier
	s_waitcnt lgkmcnt(0)
	v_mfma_f32_16x16x32_bf16 v[62:65], v[146:149], v[178:181], v[62:65]
	v_mfma_f32_16x16x32_bf16 v[58:61], v[154:157], v[178:181], v[58:61]
	v_mfma_f32_16x16x32_bf16 v[54:57], v[146:149], v[188:191], v[54:57]
	v_mfma_f32_16x16x32_bf16 v[46:49], v[154:157], v[188:191], v[46:49]
	v_mfma_f32_16x16x32_bf16 v[38:41], v[146:149], v[196:199], v[38:41]
	v_mfma_f32_16x16x32_bf16 v[30:33], v[154:157], v[196:199], v[30:33]
	v_mfma_f32_16x16x32_bf16 v[22:25], v[146:149], v[204:207], v[22:25]
	v_mfma_f32_16x16x32_bf16 v[14:17], v[154:157], v[204:207], v[14:17]
	v_mfma_f32_16x16x32_bf16 v[62:65], v[150:153], v[184:187], v[62:65]
	v_mfma_f32_16x16x32_bf16 v[58:61], v[158:161], v[184:187], v[58:61]
	v_mfma_f32_16x16x32_bf16 v[54:57], v[150:153], v[192:195], v[54:57]
	v_mfma_f32_16x16x32_bf16 v[46:49], v[158:161], v[192:195], v[46:49]
	v_mfma_f32_16x16x32_bf16 v[38:41], v[150:153], v[200:203], v[38:41]
	v_mfma_f32_16x16x32_bf16 v[30:33], v[158:161], v[200:203], v[30:33]
	v_mfma_f32_16x16x32_bf16 v[22:25], v[150:153], v[208:211], v[22:25]
	v_mfma_f32_16x16x32_bf16 v[14:17], v[158:161], v[208:211], v[14:17]
	v_mfma_f32_16x16x32_bf16 v[50:53], v[162:165], v[178:181], v[50:53]
	v_mfma_f32_16x16x32_bf16 v[42:45], v[170:173], v[178:181], v[42:45]
	v_mfma_f32_16x16x32_bf16 v[34:37], v[162:165], v[188:191], v[34:37]
	v_mfma_f32_16x16x32_bf16 v[26:29], v[170:173], v[188:191], v[26:29]
	v_mfma_f32_16x16x32_bf16 v[18:21], v[162:165], v[196:199], v[18:21]
	v_mfma_f32_16x16x32_bf16 v[10:13], v[170:173], v[196:199], v[10:13]
	v_mfma_f32_16x16x32_bf16 v[6:9], v[162:165], v[204:207], v[6:9]
	v_mfma_f32_16x16x32_bf16 v[2:5], v[170:173], v[204:207], v[2:5]
	v_mfma_f32_16x16x32_bf16 v[50:53], v[166:169], v[184:187], v[50:53]
	v_mfma_f32_16x16x32_bf16 v[42:45], v[174:177], v[184:187], v[42:45]
	v_mfma_f32_16x16x32_bf16 v[34:37], v[166:169], v[192:195], v[34:37]
	v_mfma_f32_16x16x32_bf16 v[26:29], v[174:177], v[192:195], v[26:29]
	v_mfma_f32_16x16x32_bf16 v[18:21], v[166:169], v[200:203], v[18:21]
	v_mfma_f32_16x16x32_bf16 v[10:13], v[174:177], v[200:203], v[10:13]
	v_mfma_f32_16x16x32_bf16 v[6:9], v[166:169], v[208:211], v[6:9]
	v_mfma_f32_16x16x32_bf16 v[2:5], v[174:177], v[208:211], v[2:5]
	s_barrier
	s_add_i32 s38, 0, 0x18000
	s_add_i32 s39, 0, 0x1c000
	v_add_u32_e32 v158, s38, v143
	v_add_u32_e32 v174, s39, v143
	ds_read_b128 v[146:149], v158
	ds_read_b128 v[150:153], v158 offset:1024
	ds_read_b128 v[154:157], v158 offset:2048
	ds_read_b128 v[158:161], v158 offset:3072
	ds_read_b128 v[162:165], v174
	ds_read_b128 v[166:169], v174 offset:1024
	ds_read_b128 v[170:173], v174 offset:2048
	ds_read_b128 v[174:177], v174 offset:3072
	s_add_u32 s20, s20, 0x40000
	s_addc_u32 s21, s21, 0
	s_mov_b32 m0, s25
	v_lshl_add_u64 v[218:219], s[20:21], 0, v[134:135]
	ds_read_b128 v[178:181], v145 offset:32768
	ds_read_b128 v[184:187], v145 offset:33792
	ds_read_b128 v[188:191], v145 offset:34816
	ds_read_b128 v[192:195], v145 offset:35840
	ds_read_b128 v[196:199], v145 offset:36864
	ds_read_b128 v[200:203], v145 offset:37888
	ds_read_b128 v[204:207], v145 offset:38912
	ds_read_b128 v[208:211], v145 offset:39936
	global_load_lds_dwordx4 v[218:219], off
	v_lshl_add_u64 v[218:219], s[20:21], 0, v[132:133]
	s_mov_b32 m0, s26
	s_nop 0
	global_load_lds_dwordx4 v[218:219], off
	s_waitcnt vmcnt(8)
	s_waitcnt lgkmcnt(0)
	s_barrier
	s_waitcnt lgkmcnt(0)
	v_mfma_f32_16x16x32_bf16 v[126:129], v[146:149], v[178:181], v[126:129]
	v_mfma_f32_16x16x32_bf16 v[122:125], v[154:157], v[178:181], v[122:125]
	v_mfma_f32_16x16x32_bf16 v[118:121], v[146:149], v[188:191], v[118:121]
	v_mfma_f32_16x16x32_bf16 v[110:113], v[154:157], v[188:191], v[110:113]
	v_mfma_f32_16x16x32_bf16 v[102:105], v[146:149], v[196:199], v[102:105]
	v_mfma_f32_16x16x32_bf16 v[94:97], v[154:157], v[196:199], v[94:97]
	v_mfma_f32_16x16x32_bf16 v[86:89], v[146:149], v[204:207], v[86:89]
	v_mfma_f32_16x16x32_bf16 v[78:81], v[154:157], v[204:207], v[78:81]
	v_mfma_f32_16x16x32_bf16 v[126:129], v[150:153], v[184:187], v[126:129]
	v_mfma_f32_16x16x32_bf16 v[122:125], v[158:161], v[184:187], v[122:125]
	v_mfma_f32_16x16x32_bf16 v[118:121], v[150:153], v[192:195], v[118:121]
	v_mfma_f32_16x16x32_bf16 v[110:113], v[158:161], v[192:195], v[110:113]
	v_mfma_f32_16x16x32_bf16 v[102:105], v[150:153], v[200:203], v[102:105]
	v_mfma_f32_16x16x32_bf16 v[94:97], v[158:161], v[200:203], v[94:97]
	v_mfma_f32_16x16x32_bf16 v[86:89], v[150:153], v[208:211], v[86:89]
	v_mfma_f32_16x16x32_bf16 v[78:81], v[158:161], v[208:211], v[78:81]
	v_mfma_f32_16x16x32_bf16 v[114:117], v[162:165], v[178:181], v[114:117]
	v_mfma_f32_16x16x32_bf16 v[106:109], v[170:173], v[178:181], v[106:109]
	v_mfma_f32_16x16x32_bf16 v[98:101], v[162:165], v[188:191], v[98:101]
	v_mfma_f32_16x16x32_bf16 v[90:93], v[170:173], v[188:191], v[90:93]
	v_mfma_f32_16x16x32_bf16 v[82:85], v[162:165], v[196:199], v[82:85]
	v_mfma_f32_16x16x32_bf16 v[74:77], v[170:173], v[196:199], v[74:77]
	v_mfma_f32_16x16x32_bf16 v[70:73], v[162:165], v[204:207], v[70:73]
	v_mfma_f32_16x16x32_bf16 v[66:69], v[170:173], v[204:207], v[66:69]
	v_mfma_f32_16x16x32_bf16 v[114:117], v[166:169], v[184:187], v[114:117]
	v_mfma_f32_16x16x32_bf16 v[106:109], v[174:177], v[184:187], v[106:109]
	v_mfma_f32_16x16x32_bf16 v[98:101], v[166:169], v[192:195], v[98:101]
	v_mfma_f32_16x16x32_bf16 v[90:93], v[174:177], v[192:195], v[90:93]
	v_mfma_f32_16x16x32_bf16 v[82:85], v[166:169], v[200:203], v[82:85]
	v_mfma_f32_16x16x32_bf16 v[74:77], v[174:177], v[200:203], v[74:77]
	v_mfma_f32_16x16x32_bf16 v[70:73], v[166:169], v[208:211], v[70:73]
	v_mfma_f32_16x16x32_bf16 v[66:69], v[174:177], v[208:211], v[66:69]
	s_barrier
	s_add_i32 s20, s38, s22
	v_lshl_add_u64 v[140:141], v[140:141], 0, s[74:75]
	s_mov_b32 m0, s20
	ds_read_b128 v[178:181], v145 offset:49152
	ds_read_b128 v[184:187], v145 offset:50176
	ds_read_b128 v[188:191], v145 offset:51200
	ds_read_b128 v[192:195], v145 offset:52224
	ds_read_b128 v[196:199], v145 offset:53248
	ds_read_b128 v[200:203], v145 offset:54272
	ds_read_b128 v[204:207], v145 offset:55296
	ds_read_b128 v[208:211], v145 offset:56320
	global_load_lds_dwordx4 v[140:141], off
	s_add_i32 m0, s20, 0x2000
	s_add_u32 s18, s18, 0x40080
	v_lshl_add_u64 v[140:141], v[212:213], 0, s[74:75]
	s_addc_u32 s19, s19, 0
	s_add_i32 s20, s39, s22
	global_load_lds_dwordx4 v[140:141], off
	v_lshl_add_u64 v[140:141], s[18:19], 0, v[0:1]
	s_mov_b32 m0, s20
	s_nop 0
	global_load_lds_dwordx4 v[140:141], off
	v_lshl_add_u64 v[140:141], s[18:19], 0, v[130:131]
	s_add_i32 m0, s20, 0x2000
	s_nop 0
	global_load_lds_dwordx4 v[140:141], off
	v_lshl_add_u64 v[140:141], v[214:215], 0, s[74:75]
	s_mov_b32 m0, s29
	s_nop 0
	global_load_lds_dwordx4 v[140:141], off
	v_lshl_add_u64 v[140:141], v[216:217], 0, s[74:75]
	s_mov_b32 m0, s30
	s_nop 0
	global_load_lds_dwordx4 v[140:141], off
	s_waitcnt vmcnt(8)
	s_waitcnt lgkmcnt(0)
	s_barrier
	s_waitcnt lgkmcnt(0)
	v_mfma_f32_16x16x32_bf16 v[62:65], v[146:149], v[178:181], v[62:65]
	v_mfma_f32_16x16x32_bf16 v[58:61], v[154:157], v[178:181], v[58:61]
	v_mfma_f32_16x16x32_bf16 v[54:57], v[146:149], v[188:191], v[54:57]
	v_mfma_f32_16x16x32_bf16 v[46:49], v[154:157], v[188:191], v[46:49]
	v_mfma_f32_16x16x32_bf16 v[38:41], v[146:149], v[196:199], v[38:41]
	v_mfma_f32_16x16x32_bf16 v[30:33], v[154:157], v[196:199], v[30:33]
	v_mfma_f32_16x16x32_bf16 v[22:25], v[146:149], v[204:207], v[22:25]
	v_mfma_f32_16x16x32_bf16 v[14:17], v[154:157], v[204:207], v[14:17]
	v_mfma_f32_16x16x32_bf16 v[62:65], v[150:153], v[184:187], v[62:65]
	v_mfma_f32_16x16x32_bf16 v[58:61], v[158:161], v[184:187], v[58:61]
	v_mfma_f32_16x16x32_bf16 v[54:57], v[150:153], v[192:195], v[54:57]
	v_mfma_f32_16x16x32_bf16 v[46:49], v[158:161], v[192:195], v[46:49]
	v_mfma_f32_16x16x32_bf16 v[38:41], v[150:153], v[200:203], v[38:41]
	v_mfma_f32_16x16x32_bf16 v[30:33], v[158:161], v[200:203], v[30:33]
	v_mfma_f32_16x16x32_bf16 v[22:25], v[150:153], v[208:211], v[22:25]
	v_mfma_f32_16x16x32_bf16 v[14:17], v[158:161], v[208:211], v[14:17]
	v_mfma_f32_16x16x32_bf16 v[50:53], v[162:165], v[178:181], v[50:53]
	v_mfma_f32_16x16x32_bf16 v[42:45], v[170:173], v[178:181], v[42:45]
	v_mfma_f32_16x16x32_bf16 v[34:37], v[162:165], v[188:191], v[34:37]
	v_mfma_f32_16x16x32_bf16 v[26:29], v[170:173], v[188:191], v[26:29]
	v_mfma_f32_16x16x32_bf16 v[18:21], v[162:165], v[196:199], v[18:21]
	v_mfma_f32_16x16x32_bf16 v[10:13], v[170:173], v[196:199], v[10:13]
	v_mfma_f32_16x16x32_bf16 v[6:9], v[162:165], v[204:207], v[6:9]
	v_mfma_f32_16x16x32_bf16 v[2:5], v[170:173], v[204:207], v[2:5]
	v_mfma_f32_16x16x32_bf16 v[50:53], v[166:169], v[184:187], v[50:53]
	v_mfma_f32_16x16x32_bf16 v[42:45], v[174:177], v[184:187], v[42:45]
	v_mfma_f32_16x16x32_bf16 v[34:37], v[166:169], v[192:195], v[34:37]
	v_mfma_f32_16x16x32_bf16 v[26:29], v[174:177], v[192:195], v[26:29]
	v_mfma_f32_16x16x32_bf16 v[18:21], v[166:169], v[200:203], v[18:21]
	v_mfma_f32_16x16x32_bf16 v[10:13], v[174:177], v[200:203], v[10:13]
	v_mfma_f32_16x16x32_bf16 v[6:9], v[166:169], v[208:211], v[6:9]
	v_mfma_f32_16x16x32_bf16 v[2:5], v[174:177], v[208:211], v[2:5]
	s_barrier
	s_add_i32 s37, s37, 2
	s_add_u32 s13, s13, 0x100
	s_addc_u32 s36, s36, 0
	s_add_u32 s16, s16, 0x100
	s_addc_u32 s17, s17, 0
	s_cmp_gt_u32 s37, 5
	s_cbranch_scc0 .LBB0_1327
	s_and_b64 vcc, exec, s[10:11]
	s_cbranch_vccz .LBB0_1330
	s_barrier
